# v25 + non-temporal (nt) stores for the layer-0 mixer outputs (Y), which are not re-read until the out-projection phase
# speedup vs baseline: 1.0061x; 1.0061x over previous
.LBB0_147:
	s_or_b64 exec, exec, s[0:1]
	v_readlane_b32 s48, v247, 2
	v_lshlrev_b32_e32 v24, 2, v205
	v_mov_b32_e32 v25, v155
	v_readlane_b32 s56, v247, 10
	v_readlane_b32 s57, v247, 11
	s_mov_b64 s[0:1], 0x1000
	global_load_dwordx4 v[80:83], v[64:65], off offset:2048
	v_lshl_add_u64 v[28:29], s[56:57], 0, v[24:25]
	v_add_co_u32_e32 v26, vcc, s69, v28
	v_lshl_add_u64 v[30:31], v[28:29], 0, s[0:1]
	s_nop 0
	v_addc_co_u32_e32 v27, vcc, 0, v29, vcc
	global_load_dwordx4 v[40:43], v[26:27], off offset:-4096
	global_load_dwordx4 v[36:39], v24, s[56:57]
	global_load_dwordx4 v[44:47], v[26:27], off
	s_nop 0
	global_load_dwordx4 v[24:27], v24, s[56:57] offset:16
	v_lshl_add_u64 v[28:29], v[28:29], 0, s[72:73]
	global_load_dwordx4 v[32:35], v[30:31], off offset:16
	v_add_co_u32_e32 v66, vcc, 0x2000, v64
	global_load_dwordx4 v[28:31], v[28:29], off offset:16
	s_nop 0
	v_addc_co_u32_e32 v67, vcc, 0, v65, vcc
	global_load_dwordx4 v[88:91], v[66:67], off offset:2176
	v_add_co_u32_e32 v66, vcc, 0x4000, v64
	s_mov_b64 s[40:41], vcc
	v_add_co_u32_e32 v68, vcc, 0x6000, v64
	s_mov_b64 s[42:43], vcc
	v_addc_co_u32_e64 v67, vcc, 0, v65, s[40:41]
	v_add_co_u32_e32 v70, vcc, 0x8000, v64
	s_mov_b64 s[40:41], vcc
	v_addc_co_u32_e64 v69, vcc, 0, v65, s[42:43]
	global_load_dwordx4 v[92:95], v[66:67], off offset:2304
	global_load_dwordx4 v[96:99], v[68:69], off offset:2432
	v_add_co_u32_e32 v72, vcc, s11, v64
	s_mov_b64 s[42:43], vcc
	v_addc_co_u32_e64 v71, vcc, 0, v65, s[40:41]
	v_add_co_u32_e32 v66, vcc, s12, v64
	s_mov_b64 s[40:41], vcc
	v_addc_co_u32_e64 v73, vcc, 0, v65, s[42:43]
	global_load_dwordx4 v[76:79], v[70:71], off offset:2560
	s_nop 0
	global_load_dwordx4 v[72:75], v[72:73], off offset:2688
	v_add_co_u32_e32 v64, vcc, s13, v64
	v_addc_co_u32_e64 v67, s[40:41], 0, v65, s[40:41]
	s_nop 0
	v_addc_co_u32_e32 v65, vcc, 0, v65, vcc
	global_load_dwordx4 v[68:71], v[66:67], off offset:2816
	s_nop 0
	global_load_dwordx4 v[64:67], v[64:65], off offset:2944
	s_waitcnt vmcnt(14)
	v_lshlrev_b32_e32 v102, 16, v60
	v_and_b32_e32 v103, 0xffff0000, v60
	v_lshlrev_b32_e32 v100, 16, v52
	v_and_b32_e32 v101, 0xffff0000, v52
	v_lshlrev_b32_e32 v86, 16, v48
	v_and_b32_e32 v87, 0xffff0000, v48
	v_lshlrev_b32_e32 v60, 16, v61
	v_and_b32_e32 v61, 0xffff0000, v61
	v_lshlrev_b32_e32 v52, 16, v53
	v_and_b32_e32 v53, 0xffff0000, v53
	v_lshlrev_b32_e32 v106, 16, v62
	v_and_b32_e32 v107, 0xffff0000, v62
	v_lshlrev_b32_e32 v48, 16, v49
	v_and_b32_e32 v49, 0xffff0000, v49
	v_lshlrev_b32_e32 v104, 16, v54
	v_and_b32_e32 v105, 0xffff0000, v54
	v_lshlrev_b32_e32 v108, 16, v50
	v_and_b32_e32 v109, 0xffff0000, v50
	v_lshlrev_b32_e32 v62, 16, v63
	v_and_b32_e32 v63, 0xffff0000, v63
	v_lshlrev_b32_e32 v54, 16, v55
	v_and_b32_e32 v55, 0xffff0000, v55
	v_lshl_add_u64 v[84:85], s[38:39], 0, v[154:155]
	v_readlane_b32 s49, v247, 3
	v_readlane_b32 s50, v247, 4
	v_readlane_b32 s51, v247, 5
	v_readlane_b32 s52, v247, 6
	v_readlane_b32 s53, v247, 7
	v_readlane_b32 s54, v247, 8
	v_readlane_b32 s55, v247, 9
	v_readlane_b32 s58, v247, 12
	v_readlane_b32 s59, v247, 13
	s_waitcnt vmcnt(13)
	v_lshlrev_b32_e32 v110, 16, v80
	v_and_b32_e32 v111, 0xffff0000, v80
	v_lshlrev_b32_e32 v80, 16, v81
	v_and_b32_e32 v81, 0xffff0000, v81
	s_waitcnt vmcnt(12)
	v_pk_mul_f32 v[112:113], v[40:41], v[102:103]
	v_pk_mul_f32 v[114:115], v[42:43], v[60:61]
	s_waitcnt vmcnt(11)
	v_pk_fma_f32 v[100:101], v[36:37], v[100:101], v[112:113]
	v_pk_fma_f32 v[52:53], v[38:39], v[52:53], v[114:115]
	s_waitcnt vmcnt(10)
	v_pk_fma_f32 v[100:101], v[44:45], v[86:87], v[100:101]
	v_pk_fma_f32 v[52:53], v[46:47], v[48:49], v[52:53]
	v_pk_mul_f32 v[100:101], v[100:101], v[110:111]
	s_waitcnt vmcnt(8)
	v_pk_mul_f32 v[110:111], v[32:33], v[106:107]
	v_pk_mul_f32 v[52:53], v[52:53], v[80:81]
	v_pk_fma_f32 v[104:105], v[24:25], v[104:105], v[110:111]
	v_lshlrev_b32_e32 v80, 16, v82
	v_and_b32_e32 v81, 0xffff0000, v82
	s_waitcnt vmcnt(7)
	v_pk_fma_f32 v[104:105], v[28:29], v[108:109], v[104:105]
	v_lshlrev_b32_e32 v50, 16, v83
	v_pk_mul_f32 v[80:81], v[104:105], v[80:81]
	v_lshlrev_b32_e32 v104, 16, v51
	v_and_b32_e32 v105, 0xffff0000, v51
	v_and_b32_e32 v51, 0xffff0000, v83
	v_pk_mul_f32 v[82:83], v[34:35], v[62:63]
	v_readlane_b32 s60, v247, 14
	v_pk_fma_f32 v[54:55], v[26:27], v[54:55], v[82:83]
	v_mad_i64_i32 v[82:83], s[0:1], v204, s34, v[84:85]
	v_pk_fma_f32 v[54:55], v[30:31], v[104:105], v[54:55]
	v_readlane_b32 s61, v247, 15
	v_pk_mul_f32 v[54:55], v[54:55], v[50:51]
	v_cvt_pk_bf16_f32 v50, v100, v101
	v_cvt_pk_bf16_f32 v51, v52, v53
	v_cvt_pk_bf16_f32 v52, v80, v81
	v_cvt_pk_bf16_f32 v53, v54, v55
	global_store_dwordx4 v[82:83], v[50:53], off nt
	v_lshlrev_b32_e32 v54, 16, v56
	v_and_b32_e32 v55, 0xffff0000, v56
	v_pk_mul_f32 v[52:53], v[40:41], v[86:87]
	v_pk_mul_f32 v[80:81], v[42:43], v[48:49]
	v_pk_fma_f32 v[52:53], v[36:37], v[102:103], v[52:53]
	s_waitcnt vmcnt(7)
	v_lshlrev_b32_e32 v50, 16, v88
	v_and_b32_e32 v51, 0xffff0000, v88
	v_pk_fma_f32 v[52:53], v[44:45], v[54:55], v[52:53]
	v_lshlrev_b32_e32 v56, 16, v57
	v_and_b32_e32 v57, 0xffff0000, v57
	v_pk_fma_f32 v[60:61], v[38:39], v[60:61], v[80:81]
	v_pk_mul_f32 v[50:51], v[52:53], v[50:51]
	v_lshlrev_b32_e32 v52, 16, v89
	v_and_b32_e32 v53, 0xffff0000, v89
	v_pk_fma_f32 v[60:61], v[46:47], v[56:57], v[60:61]
	v_pk_mul_f32 v[82:83], v[32:33], v[108:109]
	v_pk_mul_f32 v[52:53], v[60:61], v[52:53]
	v_lshlrev_b32_e32 v60, 16, v58
	v_and_b32_e32 v61, 0xffff0000, v58
	v_pk_fma_f32 v[82:83], v[24:25], v[106:107], v[82:83]
	v_pk_mul_f32 v[88:89], v[34:35], v[104:105]
	v_lshlrev_b32_e32 v80, 16, v90
	v_and_b32_e32 v81, 0xffff0000, v90
	v_pk_fma_f32 v[82:83], v[28:29], v[60:61], v[82:83]
	v_lshlrev_b32_e32 v58, 16, v59
	v_and_b32_e32 v59, 0xffff0000, v59
	v_pk_fma_f32 v[62:63], v[26:27], v[62:63], v[88:89]
	v_pk_mul_f32 v[80:81], v[82:83], v[80:81]
	v_lshlrev_b32_e32 v82, 16, v91
	v_and_b32_e32 v83, 0xffff0000, v91
	v_pk_fma_f32 v[62:63], v[30:31], v[58:59], v[62:63]
	v_cvt_pk_bf16_f32 v50, v50, v51
	v_pk_mul_f32 v[62:63], v[62:63], v[82:83]
	v_or_b32_e32 v82, 1, v204
	v_mad_i64_i32 v[82:83], s[0:1], v82, s34, v[84:85]
	v_cvt_pk_bf16_f32 v51, v52, v53
	v_cvt_pk_bf16_f32 v52, v80, v81
	v_cvt_pk_bf16_f32 v53, v62, v63
	v_pk_mul_f32 v[62:63], v[40:41], v[54:55]
	global_store_dwordx4 v[82:83], v[50:53], off nt
	v_pk_fma_f32 v[62:63], v[36:37], v[86:87], v[62:63]
	v_pk_mul_f32 v[80:81], v[42:43], v[56:57]
	v_lshlrev_b32_e32 v50, 16, v16
	v_and_b32_e32 v51, 0xffff0000, v16
	s_waitcnt vmcnt(7)
	v_lshlrev_b32_e32 v52, 16, v92
	v_and_b32_e32 v53, 0xffff0000, v92
	v_pk_fma_f32 v[62:63], v[44:45], v[50:51], v[62:63]
	v_pk_fma_f32 v[48:49], v[38:39], v[48:49], v[80:81]
	v_pk_mul_f32 v[52:53], v[62:63], v[52:53]
	v_lshlrev_b32_e32 v62, 16, v17
	v_and_b32_e32 v63, 0xffff0000, v17
	v_pk_mul_f32 v[82:83], v[32:33], v[60:61]
	v_lshlrev_b32_e32 v16, 16, v93
	v_and_b32_e32 v17, 0xffff0000, v93
	v_pk_fma_f32 v[48:49], v[46:47], v[62:63], v[48:49]
	v_lshlrev_b32_e32 v80, 16, v18
	v_and_b32_e32 v81, 0xffff0000, v18
	v_pk_fma_f32 v[82:83], v[24:25], v[108:109], v[82:83]
	v_lshlrev_b32_e32 v86, 16, v19
	v_and_b32_e32 v87, 0xffff0000, v19
	v_pk_mul_f32 v[18:19], v[34:35], v[58:59]
	v_pk_mul_f32 v[48:49], v[48:49], v[16:17]
	v_lshlrev_b32_e32 v16, 16, v94
	v_and_b32_e32 v17, 0xffff0000, v94
	v_pk_fma_f32 v[82:83], v[28:29], v[80:81], v[82:83]
	v_pk_fma_f32 v[18:19], v[26:27], v[104:105], v[18:19]
	v_pk_mul_f32 v[82:83], v[82:83], v[16:17]
	v_lshlrev_b32_e32 v16, 16, v95
	v_and_b32_e32 v17, 0xffff0000, v95
	v_pk_fma_f32 v[18:19], v[30:31], v[86:87], v[18:19]
	v_readlane_b32 s62, v247, 16
	v_pk_mul_f32 v[88:89], v[18:19], v[16:17]
	v_or_b32_e32 v16, 2, v204
	v_mad_i64_i32 v[90:91], s[0:1], v16, s34, v[84:85]
	v_cvt_pk_bf16_f32 v16, v52, v53
	v_cvt_pk_bf16_f32 v17, v48, v49
	v_cvt_pk_bf16_f32 v18, v82, v83
	v_cvt_pk_bf16_f32 v19, v88, v89
	global_store_dwordx4 v[90:91], v[16:19], off nt
	v_lshlrev_b32_e32 v48, 16, v20
	v_and_b32_e32 v49, 0xffff0000, v20
	v_pk_mul_f32 v[18:19], v[40:41], v[50:51]
	v_pk_mul_f32 v[52:53], v[42:43], v[62:63]
	v_pk_fma_f32 v[18:19], v[36:37], v[54:55], v[18:19]
	s_waitcnt vmcnt(7)
	v_lshlrev_b32_e32 v16, 16, v96
	v_and_b32_e32 v17, 0xffff0000, v96
	v_pk_fma_f32 v[18:19], v[44:45], v[48:49], v[18:19]
	v_lshlrev_b32_e32 v20, 16, v21
	v_and_b32_e32 v21, 0xffff0000, v21
	v_pk_fma_f32 v[52:53], v[38:39], v[56:57], v[52:53]
	v_pk_mul_f32 v[16:17], v[18:19], v[16:17]
	v_lshlrev_b32_e32 v18, 16, v97
	v_and_b32_e32 v19, 0xffff0000, v97
	v_pk_fma_f32 v[52:53], v[46:47], v[20:21], v[52:53]
	v_pk_mul_f32 v[56:57], v[32:33], v[80:81]
	v_pk_mul_f32 v[18:19], v[52:53], v[18:19]
	v_lshlrev_b32_e32 v52, 16, v22
	v_and_b32_e32 v53, 0xffff0000, v22
	v_pk_fma_f32 v[56:57], v[24:25], v[60:61], v[56:57]
	v_pk_mul_f32 v[60:61], v[34:35], v[86:87]
	v_lshlrev_b32_e32 v54, 16, v98
	v_and_b32_e32 v55, 0xffff0000, v98
	v_pk_fma_f32 v[56:57], v[28:29], v[52:53], v[56:57]
	v_lshlrev_b32_e32 v22, 16, v23
	v_and_b32_e32 v23, 0xffff0000, v23
	v_pk_fma_f32 v[58:59], v[26:27], v[58:59], v[60:61]
	v_pk_mul_f32 v[54:55], v[56:57], v[54:55]
	v_lshlrev_b32_e32 v56, 16, v99
	v_and_b32_e32 v57, 0xffff0000, v99
	v_pk_fma_f32 v[58:59], v[30:31], v[22:23], v[58:59]
	v_cvt_pk_bf16_f32 v16, v16, v17
	v_pk_mul_f32 v[56:57], v[58:59], v[56:57]
	v_or_b32_e32 v58, 3, v204
	v_mad_i64_i32 v[58:59], s[0:1], v58, s34, v[84:85]
	v_cvt_pk_bf16_f32 v17, v18, v19
	v_cvt_pk_bf16_f32 v18, v54, v55
	v_cvt_pk_bf16_f32 v19, v56, v57
	v_pk_mul_f32 v[54:55], v[40:41], v[48:49]
	global_store_dwordx4 v[58:59], v[16:19], off nt
	v_pk_fma_f32 v[50:51], v[36:37], v[50:51], v[54:55]
	v_pk_mul_f32 v[54:55], v[42:43], v[20:21]
	v_lshlrev_b32_e32 v16, 16, v8
	v_and_b32_e32 v17, 0xffff0000, v8
	s_waitcnt vmcnt(7)
	v_lshlrev_b32_e32 v18, 16, v76
	v_and_b32_e32 v19, 0xffff0000, v76
	v_pk_fma_f32 v[50:51], v[44:45], v[16:17], v[50:51]
	v_pk_fma_f32 v[54:55], v[38:39], v[62:63], v[54:55]
	v_pk_mul_f32 v[18:19], v[50:51], v[18:19]
	v_lshlrev_b32_e32 v50, 16, v9
	v_and_b32_e32 v51, 0xffff0000, v9
	v_pk_mul_f32 v[58:59], v[32:33], v[52:53]
	v_lshlrev_b32_e32 v8, 16, v77
	v_and_b32_e32 v9, 0xffff0000, v77
	v_pk_fma_f32 v[54:55], v[46:47], v[50:51], v[54:55]
	v_lshlrev_b32_e32 v56, 16, v10
	v_and_b32_e32 v57, 0xffff0000, v10
	v_pk_fma_f32 v[58:59], v[24:25], v[80:81], v[58:59]
	v_lshlrev_b32_e32 v60, 16, v11
	v_and_b32_e32 v61, 0xffff0000, v11
	v_pk_mul_f32 v[10:11], v[34:35], v[22:23]
	v_pk_mul_f32 v[54:55], v[54:55], v[8:9]
	v_lshlrev_b32_e32 v8, 16, v78
	v_and_b32_e32 v9, 0xffff0000, v78
	v_pk_fma_f32 v[58:59], v[28:29], v[56:57], v[58:59]
	v_pk_fma_f32 v[10:11], v[26:27], v[86:87], v[10:11]
	v_pk_mul_f32 v[58:59], v[58:59], v[8:9]
	v_lshlrev_b32_e32 v8, 16, v79
	v_and_b32_e32 v9, 0xffff0000, v79
	v_pk_fma_f32 v[10:11], v[30:31], v[60:61], v[10:11]
	v_readlane_b32 s63, v247, 17
	v_pk_mul_f32 v[62:63], v[10:11], v[8:9]
	v_or_b32_e32 v8, 4, v204
	v_mad_i64_i32 v[76:77], s[0:1], v8, s34, v[84:85]
	v_cvt_pk_bf16_f32 v8, v18, v19
	v_cvt_pk_bf16_f32 v9, v54, v55
	v_cvt_pk_bf16_f32 v10, v58, v59
	v_cvt_pk_bf16_f32 v11, v62, v63
	global_store_dwordx4 v[76:77], v[8:11], off nt
	v_lshlrev_b32_e32 v18, 16, v12
	v_and_b32_e32 v19, 0xffff0000, v12
	v_pk_mul_f32 v[10:11], v[40:41], v[16:17]
	s_waitcnt vmcnt(7)
	v_lshlrev_b32_e32 v8, 16, v72
	v_pk_fma_f32 v[10:11], v[36:37], v[48:49], v[10:11]
	v_pk_mul_f32 v[48:49], v[42:43], v[50:51]
	v_and_b32_e32 v9, 0xffff0000, v72
	v_pk_fma_f32 v[10:11], v[44:45], v[18:19], v[10:11]
	v_lshlrev_b32_e32 v12, 16, v13
	v_and_b32_e32 v13, 0xffff0000, v13
	v_pk_fma_f32 v[20:21], v[38:39], v[20:21], v[48:49]
	v_pk_mul_f32 v[8:9], v[10:11], v[8:9]
	v_lshlrev_b32_e32 v10, 16, v73
	v_and_b32_e32 v11, 0xffff0000, v73
	v_pk_fma_f32 v[20:21], v[46:47], v[12:13], v[20:21]
	v_pk_mul_f32 v[54:55], v[32:33], v[56:57]
	v_pk_mul_f32 v[10:11], v[20:21], v[10:11]
	v_lshlrev_b32_e32 v20, 16, v14
	v_and_b32_e32 v21, 0xffff0000, v14
	v_pk_fma_f32 v[52:53], v[24:25], v[52:53], v[54:55]
	v_pk_mul_f32 v[54:55], v[34:35], v[60:61]
	v_lshlrev_b32_e32 v48, 16, v74
	v_and_b32_e32 v49, 0xffff0000, v74
	v_pk_fma_f32 v[52:53], v[28:29], v[20:21], v[52:53]
	v_lshlrev_b32_e32 v14, 16, v15
	v_and_b32_e32 v15, 0xffff0000, v15
	v_pk_fma_f32 v[22:23], v[26:27], v[22:23], v[54:55]
	v_pk_mul_f32 v[48:49], v[52:53], v[48:49]
	v_lshlrev_b32_e32 v52, 16, v75
	v_and_b32_e32 v53, 0xffff0000, v75
	v_pk_fma_f32 v[22:23], v[30:31], v[14:15], v[22:23]
	v_cvt_pk_bf16_f32 v8, v8, v9
	v_pk_mul_f32 v[22:23], v[22:23], v[52:53]
	v_or_b32_e32 v52, 5, v204
	v_mad_i64_i32 v[52:53], s[0:1], v52, s34, v[84:85]
	v_cvt_pk_bf16_f32 v9, v10, v11
	v_cvt_pk_bf16_f32 v10, v48, v49
	v_cvt_pk_bf16_f32 v11, v22, v23
	v_pk_mul_f32 v[22:23], v[40:41], v[18:19]
	global_store_dwordx4 v[52:53], v[8:11], off nt
	v_pk_fma_f32 v[16:17], v[36:37], v[16:17], v[22:23]
	v_pk_mul_f32 v[22:23], v[42:43], v[12:13]
	v_lshlrev_b32_e32 v8, 16, v0
	v_and_b32_e32 v9, 0xffff0000, v0
	s_waitcnt vmcnt(7)
	v_lshlrev_b32_e32 v10, 16, v68
	v_and_b32_e32 v11, 0xffff0000, v68
	v_pk_fma_f32 v[16:17], v[44:45], v[8:9], v[16:17]
	v_pk_fma_f32 v[22:23], v[38:39], v[50:51], v[22:23]
	v_pk_mul_f32 v[10:11], v[16:17], v[10:11]
	v_lshlrev_b32_e32 v16, 16, v1
	v_and_b32_e32 v17, 0xffff0000, v1
	v_pk_mul_f32 v[50:51], v[32:33], v[20:21]
	v_lshlrev_b32_e32 v0, 16, v69
	v_and_b32_e32 v1, 0xffff0000, v69
	v_pk_fma_f32 v[22:23], v[46:47], v[16:17], v[22:23]
	v_lshlrev_b32_e32 v48, 16, v2
	v_and_b32_e32 v49, 0xffff0000, v2
	v_pk_fma_f32 v[50:51], v[24:25], v[56:57], v[50:51]
	v_lshlrev_b32_e32 v52, 16, v3
	v_and_b32_e32 v53, 0xffff0000, v3
	v_pk_mul_f32 v[2:3], v[34:35], v[14:15]
	v_pk_mul_f32 v[22:23], v[22:23], v[0:1]
	v_lshlrev_b32_e32 v0, 16, v70
	v_and_b32_e32 v1, 0xffff0000, v70
	v_pk_fma_f32 v[50:51], v[28:29], v[48:49], v[50:51]
	v_pk_fma_f32 v[2:3], v[26:27], v[60:61], v[2:3]
	v_pk_mul_f32 v[50:51], v[50:51], v[0:1]
	v_lshlrev_b32_e32 v0, 16, v71
	v_and_b32_e32 v1, 0xffff0000, v71
	v_pk_fma_f32 v[2:3], v[30:31], v[52:53], v[2:3]
	v_pk_mul_f32 v[8:9], v[40:41], v[8:9]
	v_pk_mul_f32 v[54:55], v[2:3], v[0:1]
	v_or_b32_e32 v0, 6, v204
	v_mad_i64_i32 v[56:57], s[0:1], v0, s34, v[84:85]
	v_cvt_pk_bf16_f32 v0, v10, v11
	v_cvt_pk_bf16_f32 v1, v22, v23
	v_cvt_pk_bf16_f32 v2, v50, v51
	v_cvt_pk_bf16_f32 v3, v54, v55
	global_store_dwordx4 v[56:57], v[0:3], off nt
	v_pk_fma_f32 v[8:9], v[36:37], v[18:19], v[8:9]
	v_pk_mul_f32 v[10:11], v[32:33], v[48:49]
	v_lshlrev_b32_e32 v0, 16, v4
	v_and_b32_e32 v1, 0xffff0000, v4
	s_waitcnt vmcnt(7)
	v_lshlrev_b32_e32 v2, 16, v64
	v_and_b32_e32 v3, 0xffff0000, v64
	v_pk_fma_f32 v[0:1], v[44:45], v[0:1], v[8:9]
	v_pk_mul_f32 v[8:9], v[42:43], v[16:17]
	v_pk_mul_f32 v[0:1], v[0:1], v[2:3]
	v_lshlrev_b32_e32 v2, 16, v5
	v_and_b32_e32 v3, 0xffff0000, v5
	v_pk_fma_f32 v[8:9], v[38:39], v[12:13], v[8:9]
	v_lshlrev_b32_e32 v4, 16, v65
	v_and_b32_e32 v5, 0xffff0000, v65
	v_pk_fma_f32 v[2:3], v[46:47], v[2:3], v[8:9]
	v_pk_fma_f32 v[10:11], v[24:25], v[20:21], v[10:11]
	v_pk_mul_f32 v[2:3], v[2:3], v[4:5]
	v_lshlrev_b32_e32 v4, 16, v6
	v_and_b32_e32 v5, 0xffff0000, v6
	v_pk_fma_f32 v[4:5], v[28:29], v[4:5], v[10:11]
	v_pk_mul_f32 v[10:11], v[34:35], v[52:53]
	v_lshlrev_b32_e32 v8, 16, v66
	v_and_b32_e32 v9, 0xffff0000, v66
	v_lshlrev_b32_e32 v6, 16, v7
	v_and_b32_e32 v7, 0xffff0000, v7
	v_pk_fma_f32 v[10:11], v[26:27], v[14:15], v[10:11]
	v_pk_mul_f32 v[4:5], v[4:5], v[8:9]
	v_lshlrev_b32_e32 v8, 16, v67
	v_and_b32_e32 v9, 0xffff0000, v67
	v_pk_fma_f32 v[6:7], v[30:31], v[6:7], v[10:11]
	v_cvt_pk_bf16_f32 v0, v0, v1
	v_pk_mul_f32 v[6:7], v[6:7], v[8:9]
	v_or_b32_e32 v8, 7, v204
	v_mad_i64_i32 v[8:9], s[0:1], v8, s34, v[84:85]
	v_cvt_pk_bf16_f32 v1, v2, v3
	v_cvt_pk_bf16_f32 v2, v4, v5
	v_cvt_pk_bf16_f32 v3, v6, v7
	global_store_dwordx4 v[8:9], v[0:3], off nt

.LBB0_181:
	s_or_b64 exec, exec, s[4:5]
	v_add_co_u32_e32 v28, vcc, 0x2000, v126
	s_waitcnt vmcnt(1)
	v_lshlrev_b32_e32 v110, 16, v48
	v_addc_co_u32_e32 v29, vcc, 0, v127, vcc
	global_load_dwordx4 v[134:137], v[126:127], off offset:2048
	global_load_dwordx4 v[76:79], v[28:29], off offset:2176
	v_add_co_u32_e32 v28, vcc, 0x4000, v126
	v_and_b32_e32 v111, 0xffff0000, v48
	v_lshlrev_b32_e32 v108, 16, v49
	v_and_b32_e32 v109, 0xffff0000, v49
	v_min_u32_e32 v48, s2, v128
	v_sub_u32_e64 v49, v206, 4 clamp
	v_addc_co_u32_e32 v29, vcc, 0, v127, vcc
	v_sub_u32_e32 v48, v48, v49
	v_add_co_u32_e32 v30, vcc, 0x6000, v126
	v_cvt_f32_i32_e32 v48, v48
	s_nop 0
	v_addc_co_u32_e32 v31, vcc, 0, v127, vcc
	global_load_dwordx4 v[72:75], v[28:29], off offset:2304
	global_load_dwordx4 v[60:63], v[30:31], off offset:2432
	v_add_co_u32_e32 v28, vcc, 0x8000, v126
	v_div_scale_f32 v49, s[4:5], v48, v48, 1.0
	s_nop 0
	v_addc_co_u32_e32 v29, vcc, 0, v127, vcc
	v_add_co_u32_e32 v30, vcc, s11, v126
	v_lshlrev_b32_e32 v104, 16, v50
	s_nop 0
	v_addc_co_u32_e32 v31, vcc, 0, v127, vcc
	v_and_b32_e32 v105, 0xffff0000, v50
	v_rcp_f32_e32 v50, v49
	v_add_co_u32_e32 v116, vcc, s12, v126
	v_lshlrev_b32_e32 v90, 16, v38
	s_nop 0
	v_addc_co_u32_e32 v117, vcc, 0, v127, vcc
	v_add_co_u32_e32 v118, vcc, s13, v126
	v_and_b32_e32 v91, 0xffff0000, v38
	v_lshlrev_b32_e32 v96, 16, v39
	v_and_b32_e32 v97, 0xffff0000, v39
	v_min_u32_e32 v38, s2, v123
	v_sub_u32_e64 v39, v114, 4 clamp
	v_addc_co_u32_e32 v119, vcc, 0, v127, vcc
	v_lshlrev_b32_e32 v102, 16, v51
	v_and_b32_e32 v103, 0xffff0000, v51
	v_fma_f32 v51, -v49, v50, 1.0
	v_sub_u32_e32 v38, v38, v39
	v_fmac_f32_e32 v50, v51, v50
	v_div_scale_f32 v51, vcc, 1.0, v48, 1.0
	v_cvt_f32_i32_e32 v38, v38
	v_lshlrev_b32_e32 v98, 16, v64
	v_and_b32_e32 v99, 0xffff0000, v64
	v_mul_f32_e32 v64, v51, v50
	v_lshlrev_b32_e32 v94, 16, v65
	v_and_b32_e32 v95, 0xffff0000, v65
	v_fma_f32 v65, -v49, v64, v51
	v_fmac_f32_e32 v64, v65, v50
	v_fma_f32 v49, -v49, v64, v51
	v_div_scale_f32 v39, s[4:5], v38, v38, 1.0
	v_lshlrev_b32_e32 v92, 16, v66
	v_and_b32_e32 v93, 0xffff0000, v66
	v_lshlrev_b32_e32 v88, 16, v67
	v_and_b32_e32 v89, 0xffff0000, v67
	v_div_fmas_f32 v49, v49, v50, v64
	s_waitcnt vmcnt(4)
	v_lshlrev_b32_e32 v66, 16, v52
	v_and_b32_e32 v67, 0xffff0000, v52
	v_lshlrev_b32_e32 v64, 16, v56
	v_and_b32_e32 v65, 0xffff0000, v56
	v_lshlrev_b32_e32 v80, 16, v53
	v_and_b32_e32 v81, 0xffff0000, v53
	v_lshlrev_b32_e32 v52, 16, v57
	v_and_b32_e32 v53, 0xffff0000, v57
	v_lshlrev_b32_e32 v56, 16, v58
	v_and_b32_e32 v57, 0xffff0000, v58
	v_rcp_f32_e32 v58, v39
	v_lshlrev_b32_e32 v100, 16, v68
	v_and_b32_e32 v101, 0xffff0000, v68
	v_lshlrev_b32_e32 v106, 16, v69
	v_and_b32_e32 v107, 0xffff0000, v69
	v_lshlrev_b32_e32 v68, 16, v54
	v_and_b32_e32 v69, 0xffff0000, v54
	v_lshlrev_b32_e32 v82, 16, v55
	v_and_b32_e32 v83, 0xffff0000, v55
	v_lshlrev_b32_e32 v54, 16, v59
	v_and_b32_e32 v55, 0xffff0000, v59
	v_fma_f32 v59, -v39, v58, 1.0
	v_fmac_f32_e32 v58, v59, v58
	v_div_scale_f32 v59, vcc, 1.0, v38, 1.0
	v_mul_f32_e32 v114, v59, v58
	v_fma_f32 v115, -v39, v114, v59
	v_fmac_f32_e32 v114, v115, v58
	v_fma_f32 v39, -v39, v114, v59
	v_div_fmas_f32 v39, v39, v58, v114
	v_div_fixup_f32 v144, v39, v38, 1.0
	v_lshlrev_b32_e32 v38, 16, v12
	v_and_b32_e32 v39, 0xffff0000, v12
	v_pk_add_f32 v[58:59], v[38:39], 0 op_sel_hi:[1,0]
	v_lshlrev_b32_e32 v84, 16, v36
	v_pk_add_f32 v[58:59], v[58:59], v[110:111]
	v_and_b32_e32 v85, 0xffff0000, v36
	v_pk_add_f32 v[58:59], v[58:59], v[98:99]
	v_div_fixup_f32 v120, v49, v48, 1.0
	v_pk_add_f32 v[58:59], v[58:59], v[84:85]
	v_lshlrev_b32_e32 v48, 16, v44
	v_pk_add_f32 v[58:59], v[58:59], v[66:67]
	v_and_b32_e32 v49, 0xffff0000, v44
	v_pk_add_f32 v[58:59], v[58:59], v[64:65]
	s_waitcnt vmcnt(3)
	v_lshlrev_b32_e32 v138, 16, v134
	v_pk_add_f32 v[58:59], v[58:59], v[48:49]
	v_and_b32_e32 v139, 0xffff0000, v134
	v_pk_add_f32 v[114:115], v[58:59], v[100:101]
	v_lshlrev_b32_e32 v12, 16, v13
	v_pk_fma_f32 v[58:59], v[120:121], v[114:115], v[66:67] op_sel_hi:[0,1,1] neg_lo:[0,0,1] neg_hi:[0,0,1]
	v_pk_mul_f32 v[58:59], v[58:59], v[138:139]
	v_and_b32_e32 v13, 0xffff0000, v13
	v_cvt_pk_bf16_f32 v134, v58, v59
	v_lshlrev_b32_e32 v58, 16, v32
	v_and_b32_e32 v59, 0xffff0000, v32
	v_pk_add_f32 v[38:39], v[58:59], v[38:39] neg_lo:[0,1] neg_hi:[0,1]
	v_lshlrev_b32_e32 v86, 16, v37
	v_pk_add_f32 v[138:139], v[114:115], v[38:39]
	s_waitcnt vmcnt(2)
	v_lshlrev_b32_e32 v38, 16, v76
	v_and_b32_e32 v39, 0xffff0000, v76
	v_pk_fma_f32 v[114:115], v[144:145], v[138:139], v[64:65] op_sel_hi:[0,1,1] neg_lo:[0,0,1] neg_hi:[0,0,1]
	v_pk_mul_f32 v[146:147], v[114:115], v[38:39]
	v_pk_add_f32 v[38:39], v[12:13], 0 op_sel_hi:[1,0]
	v_and_b32_e32 v87, 0xffff0000, v37
	v_pk_add_f32 v[38:39], v[38:39], v[108:109]
	v_lshlrev_b32_e32 v44, 16, v45
	v_pk_add_f32 v[38:39], v[38:39], v[94:95]
	v_and_b32_e32 v45, 0xffff0000, v45
	v_pk_add_f32 v[38:39], v[38:39], v[86:87]
	v_lshlrev_b32_e32 v36, 16, v135
	v_pk_add_f32 v[38:39], v[38:39], v[80:81]
	v_and_b32_e32 v37, 0xffff0000, v135
	v_pk_add_f32 v[38:39], v[38:39], v[52:53]
	v_lshlrev_b32_e32 v50, 16, v46
	v_pk_add_f32 v[38:39], v[38:39], v[44:45]
	v_and_b32_e32 v51, 0xffff0000, v46
	v_pk_add_f32 v[38:39], v[38:39], v[106:107]
	v_lshlrev_b32_e32 v112, 16, v70
	v_pk_fma_f32 v[114:115], v[120:121], v[38:39], v[80:81] op_sel_hi:[0,1,1] neg_lo:[0,0,1] neg_hi:[0,0,1]
	v_pk_mul_f32 v[36:37], v[114:115], v[36:37]
	v_lshlrev_b32_e32 v114, 16, v33
	v_and_b32_e32 v115, 0xffff0000, v33
	v_pk_add_f32 v[12:13], v[114:115], v[12:13] neg_lo:[0,1] neg_hi:[0,1]
	v_and_b32_e32 v113, 0xffff0000, v70
	v_pk_add_f32 v[148:149], v[38:39], v[12:13]
	v_lshlrev_b32_e32 v12, 16, v77
	v_and_b32_e32 v13, 0xffff0000, v77
	v_pk_fma_f32 v[32:33], v[144:145], v[148:149], v[52:53] op_sel_hi:[0,1,1] neg_lo:[0,0,1] neg_hi:[0,0,1]
	v_pk_mul_f32 v[150:151], v[32:33], v[12:13]
	v_lshlrev_b32_e32 v32, 16, v14
	v_and_b32_e32 v33, 0xffff0000, v14
	v_pk_add_f32 v[12:13], v[32:33], 0 op_sel_hi:[1,0]
	v_lshlrev_b32_e32 v140, 16, v136
	v_pk_add_f32 v[12:13], v[12:13], v[104:105]
	v_and_b32_e32 v141, 0xffff0000, v136
	v_pk_add_f32 v[12:13], v[12:13], v[92:93]
	v_lshlrev_b32_e32 v156, 16, v15
	v_pk_add_f32 v[12:13], v[12:13], v[90:91]
	v_and_b32_e32 v157, 0xffff0000, v15
	v_pk_add_f32 v[12:13], v[12:13], v[68:69]
	global_load_dwordx4 v[40:43], v[28:29], off offset:2560
	s_nop 0
	global_load_dwordx4 v[28:31], v[30:31], off offset:2688
	v_pk_add_f32 v[12:13], v[12:13], v[56:57]
	v_cvt_pk_bf16_f32 v135, v36, v37
	v_pk_add_f32 v[12:13], v[12:13], v[50:51]
	v_lshlrev_b32_e32 v46, 16, v47
	v_pk_add_f32 v[158:159], v[12:13], v[112:113]
	v_and_b32_e32 v47, 0xffff0000, v47
	v_pk_fma_f32 v[12:13], v[120:121], v[158:159], v[68:69] op_sel_hi:[0,1,1] neg_lo:[0,0,1] neg_hi:[0,0,1]
	v_pk_mul_f32 v[76:77], v[12:13], v[140:141]
	global_load_dwordx4 v[36:39], v[116:117], off offset:2816
	global_load_dwordx4 v[12:15], v[118:119], off offset:2944
	v_cvt_pk_bf16_f32 v136, v76, v77
	v_lshlrev_b32_e32 v76, 16, v34
	v_and_b32_e32 v77, 0xffff0000, v34
	v_pk_add_f32 v[32:33], v[76:77], v[32:33] neg_lo:[0,1] neg_hi:[0,1]
	v_lshlrev_b32_e32 v70, 16, v71
	v_pk_add_f32 v[118:119], v[158:159], v[32:33]
	v_pk_add_f32 v[32:33], v[156:157], 0 op_sel_hi:[1,0]
	v_and_b32_e32 v71, 0xffff0000, v71
	v_pk_add_f32 v[32:33], v[32:33], v[102:103]
	v_sub_u32_e64 v131, v131, 4 clamp
	v_pk_add_f32 v[32:33], v[32:33], v[88:89]
	v_lshlrev_b32_e32 v142, 16, v137
	v_pk_add_f32 v[32:33], v[32:33], v[96:97]
	v_and_b32_e32 v143, 0xffff0000, v137
	v_pk_add_f32 v[32:33], v[32:33], v[82:83]
	s_nop 0
	v_pk_add_f32 v[32:33], v[32:33], v[54:55]
	s_nop 0
	v_pk_add_f32 v[32:33], v[32:33], v[46:47]
	s_nop 0
	v_pk_add_f32 v[140:141], v[32:33], v[70:71]
	s_nop 0
	v_pk_fma_f32 v[32:33], v[120:121], v[140:141], v[82:83] op_sel_hi:[0,1,1] neg_lo:[0,0,1] neg_hi:[0,0,1]
	v_min_u32_e32 v120, s2, v122
	v_sub_u32_e32 v120, v120, v131
	v_pk_mul_f32 v[116:117], v[32:33], v[142:143]
	v_mov_b64_e32 v[32:33], s[38:39]
	v_cvt_f32_i32_e32 v120, v120
	v_cvt_pk_bf16_f32 v137, v116, v117
	v_mad_i64_i32 v[116:117], s[4:5], v204, s34, v[32:33]
	v_lshl_add_u64 v[116:117], v[116:117], 0, v[154:155]
	global_store_dwordx4 v[116:117], v[134:137], off offset:2048 nt
	v_lshlrev_b32_e32 v116, 16, v78
	v_and_b32_e32 v117, 0xffff0000, v78
	v_pk_fma_f32 v[134:135], v[144:145], v[118:119], v[56:57] op_sel_hi:[0,1,1] neg_lo:[0,0,1] neg_hi:[0,0,1]
	v_pk_mul_f32 v[136:137], v[134:135], v[116:117]
	v_lshlrev_b32_e32 v116, 16, v35
	v_and_b32_e32 v117, 0xffff0000, v35
	v_div_scale_f32 v131, s[4:5], v120, v120, 1.0
	v_pk_add_f32 v[34:35], v[116:117], v[156:157] neg_lo:[0,1] neg_hi:[0,1]
	v_rcp_f32_e32 v142, v131
	v_pk_add_f32 v[140:141], v[140:141], v[34:35]
	v_lshlrev_b32_e32 v34, 16, v79
	v_and_b32_e32 v35, 0xffff0000, v79
	v_pk_fma_f32 v[78:79], v[144:145], v[140:141], v[54:55] op_sel_hi:[0,1,1] neg_lo:[0,0,1] neg_hi:[0,0,1]
	v_pk_mul_f32 v[34:35], v[78:79], v[34:35]
	v_or_b32_e32 v78, 1, v204
	v_cvt_pk_bf16_f32 v136, v136, v137
	v_cvt_pk_bf16_f32 v137, v34, v35
	v_fma_f32 v34, -v131, v142, 1.0
	v_mad_i64_i32 v[78:79], s[4:5], v78, s34, v[32:33]
	v_fmac_f32_e32 v142, v34, v142
	v_div_scale_f32 v34, vcc, 1.0, v120, 1.0
	v_lshl_add_u64 v[78:79], v[78:79], 0, v[154:155]
	v_cvt_pk_bf16_f32 v134, v146, v147
	v_cvt_pk_bf16_f32 v135, v150, v151
	v_mul_f32_e32 v35, v34, v142
	global_store_dwordx4 v[78:79], v[134:137], off offset:2048 nt
	v_fma_f32 v78, -v131, v35, v34
	v_fmac_f32_e32 v35, v78, v142
	v_fma_f32 v34, -v131, v35, v34
	v_div_fmas_f32 v34, v34, v142, v35
	v_div_fixup_f32 v120, v34, v120, 1.0
	v_lshlrev_b32_e32 v34, 16, v24
	v_and_b32_e32 v35, 0xffff0000, v24
	v_pk_add_f32 v[78:79], v[34:35], v[110:111] neg_lo:[0,1] neg_hi:[0,1]
	s_nop 0
	v_pk_add_f32 v[134:135], v[138:139], v[78:79]
	s_waitcnt vmcnt(7)
	v_lshlrev_b32_e32 v78, 16, v72
	v_and_b32_e32 v79, 0xffff0000, v72
	v_pk_fma_f32 v[110:111], v[120:121], v[134:135], v[48:49] op_sel_hi:[0,1,1] neg_lo:[0,0,1] neg_hi:[0,0,1]
	v_pk_mul_f32 v[136:137], v[110:111], v[78:79]
	v_lshlrev_b32_e32 v110, 16, v25
	v_and_b32_e32 v111, 0xffff0000, v25
	v_pk_add_f32 v[24:25], v[110:111], v[108:109] neg_lo:[0,1] neg_hi:[0,1]
	v_lshlrev_b32_e32 v108, 16, v26
	v_pk_add_f32 v[138:139], v[148:149], v[24:25]
	v_lshlrev_b32_e32 v24, 16, v73
	v_and_b32_e32 v25, 0xffff0000, v73
	v_pk_fma_f32 v[72:73], v[120:121], v[138:139], v[44:45] op_sel_hi:[0,1,1] neg_lo:[0,0,1] neg_hi:[0,0,1]
	v_and_b32_e32 v109, 0xffff0000, v26
	v_pk_mul_f32 v[72:73], v[72:73], v[24:25]
	v_pk_add_f32 v[24:25], v[108:109], v[104:105] neg_lo:[0,1] neg_hi:[0,1]
	s_nop 0
	v_pk_add_f32 v[104:105], v[118:119], v[24:25]
	v_lshlrev_b32_e32 v24, 16, v74
	v_and_b32_e32 v25, 0xffff0000, v74
	v_pk_fma_f32 v[78:79], v[120:121], v[104:105], v[50:51] op_sel_hi:[0,1,1] neg_lo:[0,0,1] neg_hi:[0,0,1]
	v_pk_mul_f32 v[118:119], v[78:79], v[24:25]
	v_lshlrev_b32_e32 v78, 16, v27
	v_and_b32_e32 v79, 0xffff0000, v27
	v_pk_add_f32 v[24:25], v[78:79], v[102:103] neg_lo:[0,1] neg_hi:[0,1]
	s_nop 0
	v_pk_add_f32 v[102:103], v[140:141], v[24:25]
	v_lshlrev_b32_e32 v24, 16, v75
	v_and_b32_e32 v25, 0xffff0000, v75
	v_pk_fma_f32 v[26:27], v[120:121], v[102:103], v[46:47] op_sel_hi:[0,1,1] neg_lo:[0,0,1] neg_hi:[0,0,1]
	v_pk_mul_f32 v[74:75], v[26:27], v[24:25]
	v_or_b32_e32 v24, 2, v204
	v_mad_i64_i32 v[24:25], s[4:5], v24, s34, v[32:33]
	v_lshl_add_u64 v[140:141], v[24:25], 0, v[154:155]
	v_min_u32_e32 v24, s2, v121
	v_sub_u32_e64 v25, v129, 4 clamp
	v_sub_u32_e32 v24, v24, v25
	v_cvt_f32_i32_e32 v120, v24
	v_cvt_pk_bf16_f32 v25, v72, v73
	v_cvt_pk_bf16_f32 v24, v136, v137
	v_cvt_pk_bf16_f32 v26, v118, v119
	v_div_scale_f32 v72, s[4:5], v120, v120, 1.0
	v_rcp_f32_e32 v73, v72
	v_cvt_pk_bf16_f32 v27, v74, v75
	global_store_dwordx4 v[140:141], v[24:27], off offset:2048 nt
	s_nop 1
	v_fma_f32 v24, -v72, v73, 1.0
	v_fmac_f32_e32 v73, v24, v73
	v_div_scale_f32 v24, vcc, 1.0, v120, 1.0
	v_mul_f32_e32 v25, v24, v73
	v_fma_f32 v26, -v72, v25, v24
	v_fmac_f32_e32 v25, v26, v73
	v_fma_f32 v24, -v72, v25, v24
	v_lshlrev_b32_e32 v26, 16, v20
	v_and_b32_e32 v27, 0xffff0000, v20
	v_div_fmas_f32 v24, v24, v73, v25
	v_pk_add_f32 v[72:73], v[26:27], v[98:99] neg_lo:[0,1] neg_hi:[0,1]
	v_div_fixup_f32 v24, v24, v120, 1.0
	v_pk_add_f32 v[98:99], v[134:135], v[72:73]
	s_waitcnt vmcnt(7)
	v_lshlrev_b32_e32 v72, 16, v60
	v_and_b32_e32 v73, 0xffff0000, v60
	v_pk_fma_f32 v[74:75], v[24:25], v[98:99], v[100:101] op_sel_hi:[0,1,1] neg_lo:[0,0,1] neg_hi:[0,0,1]
	v_pk_mul_f32 v[100:101], v[74:75], v[72:73]
	v_lshlrev_b32_e32 v74, 16, v21
	v_and_b32_e32 v75, 0xffff0000, v21
	v_pk_add_f32 v[20:21], v[74:75], v[94:95] neg_lo:[0,1] neg_hi:[0,1]
	v_lshlrev_b32_e32 v72, 16, v22
	v_pk_add_f32 v[94:95], v[138:139], v[20:21]
	v_lshlrev_b32_e32 v20, 16, v61
	v_and_b32_e32 v21, 0xffff0000, v61
	v_pk_fma_f32 v[60:61], v[24:25], v[94:95], v[106:107] op_sel_hi:[0,1,1] neg_lo:[0,0,1] neg_hi:[0,0,1]
	v_and_b32_e32 v73, 0xffff0000, v22
	v_pk_mul_f32 v[106:107], v[60:61], v[20:21]
	v_pk_add_f32 v[20:21], v[72:73], v[92:93] neg_lo:[0,1] neg_hi:[0,1]
	s_nop 0
	v_pk_add_f32 v[92:93], v[104:105], v[20:21]
	v_lshlrev_b32_e32 v20, 16, v62
	v_and_b32_e32 v21, 0xffff0000, v62
	v_pk_fma_f32 v[60:61], v[24:25], v[92:93], v[112:113] op_sel_hi:[0,1,1] neg_lo:[0,0,1] neg_hi:[0,0,1]
	v_pk_mul_f32 v[104:105], v[60:61], v[20:21]
	v_lshlrev_b32_e32 v60, 16, v23
	v_and_b32_e32 v61, 0xffff0000, v23
	v_pk_add_f32 v[20:21], v[60:61], v[88:89] neg_lo:[0,1] neg_hi:[0,1]
	s_nop 0
	v_pk_add_f32 v[88:89], v[102:103], v[20:21]
	v_lshlrev_b32_e32 v20, 16, v63
	v_and_b32_e32 v21, 0xffff0000, v63
	v_pk_fma_f32 v[22:23], v[24:25], v[88:89], v[70:71] op_sel_hi:[0,1,1] neg_lo:[0,0,1] neg_hi:[0,0,1]
	v_pk_mul_f32 v[24:25], v[22:23], v[20:21]
	v_or_b32_e32 v20, 3, v204
	v_mad_i64_i32 v[20:21], s[4:5], v20, s34, v[32:33]
	v_lshl_add_u64 v[62:63], v[20:21], 0, v[154:155]
	v_min_u32_e32 v20, s2, v133
	v_sub_u32_e32 v20, v20, v128
	v_add_u32_e32 v20, 4, v20
	v_cvt_f32_i32_e32 v70, v20
	v_cvt_pk_bf16_f32 v20, v100, v101
	v_cvt_pk_bf16_f32 v21, v106, v107
	v_cvt_pk_bf16_f32 v22, v104, v105
	v_div_scale_f32 v71, s[4:5], v70, v70, 1.0
	v_rcp_f32_e32 v100, v71
	v_cvt_pk_bf16_f32 v23, v24, v25
	global_store_dwordx4 v[62:63], v[20:23], off offset:2048 nt
	s_nop 1
	v_fma_f32 v20, -v71, v100, 1.0
	v_fmac_f32_e32 v100, v20, v100
	v_div_scale_f32 v20, vcc, 1.0, v70, 1.0
	v_mul_f32_e32 v21, v20, v100
	v_fma_f32 v22, -v71, v21, v20
	v_fmac_f32_e32 v21, v22, v100
	v_fma_f32 v20, -v71, v21, v20
	v_div_fmas_f32 v20, v20, v100, v21
	v_div_fixup_f32 v62, v20, v70, 1.0
	v_lshlrev_b32_e32 v20, 16, v16
	v_and_b32_e32 v21, 0xffff0000, v16
	v_pk_add_f32 v[22:23], v[20:21], v[84:85] neg_lo:[0,1] neg_hi:[0,1]
	s_nop 0
	v_pk_add_f32 v[70:71], v[98:99], v[22:23]
	s_waitcnt vmcnt(7)
	v_lshlrev_b32_e32 v22, 16, v40
	v_and_b32_e32 v23, 0xffff0000, v40
	v_pk_fma_f32 v[24:25], v[62:63], v[70:71], v[58:59] op_sel_hi:[0,1,1] neg_lo:[0,0,1] neg_hi:[0,0,1]
	v_pk_mul_f32 v[58:59], v[24:25], v[22:23]
	v_lshlrev_b32_e32 v24, 16, v17
	v_and_b32_e32 v25, 0xffff0000, v17
	v_pk_add_f32 v[16:17], v[24:25], v[86:87] neg_lo:[0,1] neg_hi:[0,1]
	s_nop 0
	v_pk_add_f32 v[84:85], v[94:95], v[16:17]
	v_lshlrev_b32_e32 v16, 16, v41
	v_and_b32_e32 v17, 0xffff0000, v41
	v_pk_fma_f32 v[22:23], v[62:63], v[84:85], v[114:115] op_sel_hi:[0,1,1] neg_lo:[0,0,1] neg_hi:[0,0,1]
	v_pk_mul_f32 v[86:87], v[22:23], v[16:17]
	v_lshlrev_b32_e32 v22, 16, v18
	v_and_b32_e32 v23, 0xffff0000, v18
	v_pk_add_f32 v[16:17], v[22:23], v[90:91] neg_lo:[0,1] neg_hi:[0,1]
	s_nop 0
	v_pk_add_f32 v[90:91], v[92:93], v[16:17]
	v_lshlrev_b32_e32 v16, 16, v42
	v_and_b32_e32 v17, 0xffff0000, v42
	v_pk_fma_f32 v[40:41], v[62:63], v[90:91], v[76:77] op_sel_hi:[0,1,1] neg_lo:[0,0,1] neg_hi:[0,0,1]
	v_pk_mul_f32 v[76:77], v[40:41], v[16:17]
	v_lshlrev_b32_e32 v16, 16, v19
	v_and_b32_e32 v17, 0xffff0000, v19
	v_pk_add_f32 v[18:19], v[16:17], v[96:97] neg_lo:[0,1] neg_hi:[0,1]
	v_lshlrev_b32_e32 v40, 16, v43
	v_pk_add_f32 v[18:19], v[88:89], v[18:19]
	v_and_b32_e32 v41, 0xffff0000, v43
	v_pk_fma_f32 v[42:43], v[62:63], v[18:19], v[116:117] op_sel_hi:[0,1,1] neg_lo:[0,0,1] neg_hi:[0,0,1]
	v_pk_mul_f32 v[62:63], v[42:43], v[40:41]
	v_or_b32_e32 v40, 4, v204
	v_mad_i64_i32 v[40:41], s[4:5], v40, s34, v[32:33]
	v_lshl_add_u64 v[88:89], v[40:41], 0, v[154:155]
	v_min_u32_e32 v40, s2, v132
	v_sub_u32_e32 v40, v40, v123
	v_add_u32_e32 v40, 4, v40
	v_cvt_f32_i32_e32 v92, v40
	v_cvt_pk_bf16_f32 v40, v58, v59
	v_cvt_pk_bf16_f32 v41, v86, v87
	v_cvt_pk_bf16_f32 v42, v76, v77
	v_div_scale_f32 v58, s[4:5], v92, v92, 1.0
	v_rcp_f32_e32 v59, v58
	v_cvt_pk_bf16_f32 v43, v62, v63
	global_store_dwordx4 v[88:89], v[40:43], off offset:2048 nt
	s_nop 1
	v_fma_f32 v40, -v58, v59, 1.0
	v_fmac_f32_e32 v59, v40, v59
	v_div_scale_f32 v40, vcc, 1.0, v92, 1.0
	v_mul_f32_e32 v41, v40, v59
	v_fma_f32 v42, -v58, v41, v40
	v_fmac_f32_e32 v41, v42, v59
	v_fma_f32 v40, -v58, v41, v40
	v_lshlrev_b32_e32 v42, 16, v8
	v_and_b32_e32 v43, 0xffff0000, v8
	v_div_fmas_f32 v40, v40, v59, v41
	v_pk_add_f32 v[42:43], v[42:43], v[66:67] neg_lo:[0,1] neg_hi:[0,1]
	v_div_fixup_f32 v40, v40, v92, 1.0
	v_pk_add_f32 v[42:43], v[70:71], v[42:43]
	v_lshlrev_b32_e32 v8, 16, v9
	v_and_b32_e32 v9, 0xffff0000, v9
	s_waitcnt vmcnt(7)
	v_lshlrev_b32_e32 v58, 16, v28
	v_and_b32_e32 v59, 0xffff0000, v28
	v_pk_fma_f32 v[34:35], v[40:41], v[42:43], v[34:35] op_sel_hi:[0,1,1] neg_lo:[0,0,1] neg_hi:[0,0,1]
	v_pk_add_f32 v[8:9], v[8:9], v[80:81] neg_lo:[0,1] neg_hi:[0,1]
	v_pk_mul_f32 v[34:35], v[34:35], v[58:59]
	v_pk_add_f32 v[58:59], v[84:85], v[8:9]
	v_lshlrev_b32_e32 v8, 16, v29
	v_and_b32_e32 v9, 0xffff0000, v29
	v_pk_fma_f32 v[28:29], v[40:41], v[58:59], v[110:111] op_sel_hi:[0,1,1] neg_lo:[0,0,1] neg_hi:[0,0,1]
	v_pk_mul_f32 v[28:29], v[28:29], v[8:9]
	v_lshlrev_b32_e32 v8, 16, v10
	v_and_b32_e32 v9, 0xffff0000, v10
	v_pk_add_f32 v[8:9], v[8:9], v[68:69] neg_lo:[0,1] neg_hi:[0,1]
	s_nop 0
	v_pk_add_f32 v[62:63], v[90:91], v[8:9]
	v_lshlrev_b32_e32 v8, 16, v30
	v_and_b32_e32 v9, 0xffff0000, v30
	v_pk_fma_f32 v[66:67], v[40:41], v[62:63], v[108:109] op_sel_hi:[0,1,1] neg_lo:[0,0,1] neg_hi:[0,0,1]
	v_pk_mul_f32 v[66:67], v[66:67], v[8:9]
	v_lshlrev_b32_e32 v8, 16, v11
	v_and_b32_e32 v9, 0xffff0000, v11
	v_pk_add_f32 v[8:9], v[8:9], v[82:83] neg_lo:[0,1] neg_hi:[0,1]
	s_nop 0
	v_pk_add_f32 v[18:19], v[18:19], v[8:9]
	v_lshlrev_b32_e32 v8, 16, v31
	v_and_b32_e32 v9, 0xffff0000, v31
	v_pk_fma_f32 v[10:11], v[40:41], v[18:19], v[78:79] op_sel_hi:[0,1,1] neg_lo:[0,0,1] neg_hi:[0,0,1]
	v_pk_mul_f32 v[30:31], v[10:11], v[8:9]
	v_or_b32_e32 v8, 5, v204
	v_mad_i64_i32 v[8:9], s[4:5], v8, s34, v[32:33]
	v_lshl_add_u64 v[40:41], v[8:9], 0, v[154:155]
	v_min_u32_e32 v8, s2, v130
	v_sub_u32_e32 v8, v8, v122
	v_add_u32_e32 v8, 4, v8
	v_cvt_f32_i32_e32 v68, v8
	v_cvt_pk_bf16_f32 v9, v28, v29
	v_cvt_pk_bf16_f32 v8, v34, v35
	v_cvt_pk_bf16_f32 v10, v66, v67
	v_div_scale_f32 v28, s[4:5], v68, v68, 1.0
	v_rcp_f32_e32 v29, v28
	v_cvt_pk_bf16_f32 v11, v30, v31
	global_store_dwordx4 v[40:41], v[8:11], off offset:2048 nt
	s_nop 1
	v_fma_f32 v8, -v28, v29, 1.0
	v_fmac_f32_e32 v29, v8, v29
	v_div_scale_f32 v8, vcc, 1.0, v68, 1.0
	v_mul_f32_e32 v9, v8, v29
	v_fma_f32 v10, -v28, v9, v8
	v_fmac_f32_e32 v9, v10, v29
	v_fma_f32 v8, -v28, v9, v8
	v_lshlrev_b32_e32 v10, 16, v4
	v_and_b32_e32 v11, 0xffff0000, v4
	v_div_fmas_f32 v8, v8, v29, v9
	v_pk_add_f32 v[10:11], v[10:11], v[64:65] neg_lo:[0,1] neg_hi:[0,1]
	v_div_fixup_f32 v8, v8, v68, 1.0
	v_pk_add_f32 v[10:11], v[42:43], v[10:11]
	v_lshlrev_b32_e32 v4, 16, v5
	v_and_b32_e32 v5, 0xffff0000, v5
	s_waitcnt vmcnt(7)
	v_lshlrev_b32_e32 v28, 16, v36
	v_and_b32_e32 v29, 0xffff0000, v36
	v_pk_fma_f32 v[26:27], v[8:9], v[10:11], v[26:27] op_sel_hi:[0,1,1] neg_lo:[0,0,1] neg_hi:[0,0,1]
	v_pk_add_f32 v[4:5], v[4:5], v[52:53] neg_lo:[0,1] neg_hi:[0,1]
	v_pk_mul_f32 v[26:27], v[26:27], v[28:29]
	v_pk_add_f32 v[28:29], v[58:59], v[4:5]
	v_lshlrev_b32_e32 v4, 16, v37
	v_and_b32_e32 v5, 0xffff0000, v37
	v_pk_fma_f32 v[30:31], v[8:9], v[28:29], v[74:75] op_sel_hi:[0,1,1] neg_lo:[0,0,1] neg_hi:[0,0,1]
	v_pk_mul_f32 v[30:31], v[30:31], v[4:5]
	v_lshlrev_b32_e32 v4, 16, v6
	v_and_b32_e32 v5, 0xffff0000, v6
	v_pk_add_f32 v[4:5], v[4:5], v[56:57] neg_lo:[0,1] neg_hi:[0,1]
	s_nop 0
	v_pk_add_f32 v[34:35], v[62:63], v[4:5]
	v_lshlrev_b32_e32 v4, 16, v38
	v_and_b32_e32 v5, 0xffff0000, v38
	v_pk_fma_f32 v[36:37], v[8:9], v[34:35], v[72:73] op_sel_hi:[0,1,1] neg_lo:[0,0,1] neg_hi:[0,0,1]
	v_pk_mul_f32 v[36:37], v[36:37], v[4:5]
	v_lshlrev_b32_e32 v4, 16, v7
	v_and_b32_e32 v5, 0xffff0000, v7
	v_pk_add_f32 v[4:5], v[4:5], v[54:55] neg_lo:[0,1] neg_hi:[0,1]
	s_nop 0
	v_pk_add_f32 v[18:19], v[18:19], v[4:5]
	v_lshlrev_b32_e32 v4, 16, v39
	v_and_b32_e32 v5, 0xffff0000, v39
	v_pk_fma_f32 v[6:7], v[8:9], v[18:19], v[60:61] op_sel_hi:[0,1,1] neg_lo:[0,0,1] neg_hi:[0,0,1]
	v_pk_mul_f32 v[8:9], v[6:7], v[4:5]
	v_or_b32_e32 v4, 6, v204
	v_mad_i64_i32 v[4:5], s[4:5], v4, s34, v[32:33]
	v_lshl_add_u64 v[38:39], v[4:5], 0, v[154:155]
	v_add_u32_e32 v4, 11, v206
	v_min_u32_e32 v4, s2, v4
	v_sub_u32_e32 v4, v4, v121
	v_add_u32_e32 v4, 4, v4
	v_cvt_f32_i32_e32 v40, v4
	v_cvt_pk_bf16_f32 v4, v26, v27
	v_cvt_pk_bf16_f32 v5, v30, v31
	v_cvt_pk_bf16_f32 v6, v36, v37
	v_div_scale_f32 v26, s[4:5], v40, v40, 1.0
	v_rcp_f32_e32 v27, v26
	v_cvt_pk_bf16_f32 v7, v8, v9
	global_store_dwordx4 v[38:39], v[4:7], off offset:2048 nt
	s_waitcnt vmcnt(7)
	v_lshlrev_b32_e32 v8, 16, v12
	v_and_b32_e32 v9, 0xffff0000, v12
	v_fma_f32 v4, -v26, v27, 1.0
	v_fmac_f32_e32 v27, v4, v27
	v_div_scale_f32 v4, vcc, 1.0, v40, 1.0
	v_mul_f32_e32 v5, v4, v27
	v_fma_f32 v6, -v26, v5, v4
	v_fmac_f32_e32 v5, v6, v27
	v_fma_f32 v4, -v26, v5, v4
	v_lshlrev_b32_e32 v6, 16, v0
	v_and_b32_e32 v7, 0xffff0000, v0
	v_div_fmas_f32 v4, v4, v27, v5
	v_pk_add_f32 v[6:7], v[6:7], v[48:49] neg_lo:[0,1] neg_hi:[0,1]
	v_lshlrev_b32_e32 v0, 16, v1
	v_and_b32_e32 v1, 0xffff0000, v1
	v_div_fixup_f32 v4, v4, v40, 1.0
	v_pk_add_f32 v[6:7], v[10:11], v[6:7]
	v_pk_add_f32 v[0:1], v[0:1], v[44:45] neg_lo:[0,1] neg_hi:[0,1]
	v_pk_fma_f32 v[6:7], v[4:5], v[6:7], v[20:21] op_sel_hi:[0,1,1] neg_lo:[0,0,1] neg_hi:[0,0,1]
	v_pk_add_f32 v[0:1], v[28:29], v[0:1]
	v_pk_mul_f32 v[6:7], v[6:7], v[8:9]
	v_lshlrev_b32_e32 v8, 16, v13
	v_and_b32_e32 v9, 0xffff0000, v13
	v_pk_fma_f32 v[0:1], v[4:5], v[0:1], v[24:25] op_sel_hi:[0,1,1] neg_lo:[0,0,1] neg_hi:[0,0,1]
	v_pk_mul_f32 v[8:9], v[0:1], v[8:9]
	v_lshlrev_b32_e32 v0, 16, v2
	v_and_b32_e32 v1, 0xffff0000, v2
	v_pk_add_f32 v[0:1], v[0:1], v[50:51] neg_lo:[0,1] neg_hi:[0,1]
	v_lshlrev_b32_e32 v10, 16, v14
	v_pk_add_f32 v[0:1], v[34:35], v[0:1]
	v_and_b32_e32 v11, 0xffff0000, v14
	v_pk_fma_f32 v[0:1], v[4:5], v[0:1], v[22:23] op_sel_hi:[0,1,1] neg_lo:[0,0,1] neg_hi:[0,0,1]
	v_pk_mul_f32 v[10:11], v[0:1], v[10:11]
	v_lshlrev_b32_e32 v0, 16, v3
	v_and_b32_e32 v1, 0xffff0000, v3
	v_pk_add_f32 v[0:1], v[0:1], v[46:47] neg_lo:[0,1] neg_hi:[0,1]
	v_lshlrev_b32_e32 v2, 16, v15
	v_pk_add_f32 v[0:1], v[18:19], v[0:1]
	v_and_b32_e32 v3, 0xffff0000, v15
	v_pk_fma_f32 v[0:1], v[4:5], v[0:1], v[16:17] op_sel_hi:[0,1,1] neg_lo:[0,0,1] neg_hi:[0,0,1]
	v_pk_mul_f32 v[4:5], v[0:1], v[2:3]
	v_or_b32_e32 v0, 7, v204
	v_mad_i64_i32 v[0:1], s[4:5], v0, s34, v[32:33]
	v_lshl_add_u64 v[12:13], v[0:1], 0, v[154:155]
	v_cvt_pk_bf16_f32 v0, v6, v7
	v_cvt_pk_bf16_f32 v1, v8, v9
	v_cvt_pk_bf16_f32 v2, v10, v11
	v_cvt_pk_bf16_f32 v3, v4, v5
	s_mov_b64 s[4:5], 0
	global_store_dwordx4 v[12:13], v[0:3], off offset:2048 nt

.LBB0_204:
	s_or_b64 exec, exec, s[6:7]
	global_load_dwordx4 v[68:71], v[126:127], off offset:2048
	v_add_co_u32_e32 v20, vcc, 0x2000, v126
	s_mov_b64 s[40:41], vcc
	v_min_u32_e32 v21, s2, v96
	v_sub_u32_e64 v23, v206, 2 clamp
	v_add_co_u32_e32 v22, vcc, 0x4000, v126
	s_mov_b64 s[42:43], vcc
	v_sub_u32_e32 v23, v21, v23
	v_addc_co_u32_e64 v21, vcc, 0, v127, s[40:41]
	global_load_dwordx4 v[98:101], v[20:21], off offset:2176
	s_waitcnt vmcnt(2)
	v_lshlrev_b32_e32 v74, 16, v44
	v_and_b32_e32 v75, 0xffff0000, v44
	v_add_co_u32_e32 v40, vcc, 0x6000, v126
	v_cvt_f32_i32_e32 v44, v23
	s_mov_b64 s[40:41], vcc
	v_addc_co_u32_e64 v23, vcc, 0, v127, s[42:43]
	v_add_co_u32_e32 v20, vcc, 0x8000, v126
	s_mov_b64 s[42:43], vcc
	v_addc_co_u32_e64 v41, vcc, 0, v127, s[40:41]
	v_lshlrev_b32_e32 v88, 16, v36
	v_and_b32_e32 v89, 0xffff0000, v36
	v_lshlrev_b32_e32 v72, 16, v48
	v_and_b32_e32 v73, 0xffff0000, v48
	v_add_co_u32_e32 v42, vcc, s11, v126
	v_div_scale_f32 v48, s[6:7], v44, v44, 1.0
	v_lshlrev_b32_e32 v76, 16, v32
	v_and_b32_e32 v77, 0xffff0000, v32
	v_lshlrev_b32_e32 v80, 16, v33
	v_and_b32_e32 v81, 0xffff0000, v33
	v_pk_add_f32 v[32:33], v[88:89], 0 op_sel_hi:[1,0]
	s_mov_b64 s[40:41], vcc
	v_addc_co_u32_e64 v21, vcc, 0, v127, s[42:43]
	v_rcp_f32_e32 v82, v48
	v_pk_add_f32 v[32:33], v[32:33], v[76:77]
	global_load_dwordx4 v[64:67], v[22:23], off offset:2304
	global_load_dwordx4 v[60:63], v[40:41], off offset:2432
	v_add_co_u32_e32 v22, vcc, s12, v126
	v_pk_add_f32 v[32:33], v[32:33], v[74:75]
	s_mov_b64 s[42:43], vcc
	v_addc_co_u32_e64 v43, vcc, 0, v127, s[40:41]
	v_pk_add_f32 v[104:105], v[32:33], v[72:73]
	v_add_co_u32_e32 v32, vcc, s13, v126
	v_addc_co_u32_e64 v23, s[42:43], 0, v127, s[42:43]
	global_load_dwordx4 v[56:59], v[20:21], off offset:2560
	global_load_dwordx4 v[52:55], v[42:43], off offset:2688
	v_addc_co_u32_e32 v33, vcc, 0, v127, vcc
	global_load_dwordx4 v[40:43], v[22:23], off offset:2816
	s_nop 0
	global_load_dwordx4 v[20:23], v[32:33], off offset:2944
	v_fma_f32 v32, -v48, v82, 1.0
	v_div_scale_f32 v79, s[40:41], 1.0, v44, 1.0
	v_fmac_f32_e32 v82, v32, v82
	v_mul_f32_e32 v32, v79, v82
	v_fma_f32 v33, -v48, v32, v79
	v_fmac_f32_e32 v32, v33, v82
	v_fma_f32 v33, -v48, v32, v79
	s_mov_b64 vcc, s[40:41]
	v_div_fmas_f32 v32, v33, v82, v32
	v_lshlrev_b32_e32 v102, 16, v37
	v_and_b32_e32 v103, 0xffff0000, v37
	v_div_fixup_f32 v32, v32, v44, 1.0
	v_pk_add_f32 v[36:37], v[102:103], 0 op_sel_hi:[1,0]
	v_pk_fma_f32 v[82:83], v[32:33], v[104:105], v[74:75] op_sel_hi:[0,1,1] neg_lo:[0,0,1] neg_hi:[0,0,1]
	v_pk_add_f32 v[36:37], v[36:37], v[80:81]
	v_lshlrev_b32_e32 v108, 16, v38
	v_and_b32_e32 v109, 0xffff0000, v38
	v_lshlrev_b32_e32 v110, 16, v34
	v_and_b32_e32 v111, 0xffff0000, v34
	s_waitcnt vmcnt(7)
	v_lshlrev_b32_e32 v84, 16, v68
	v_and_b32_e32 v85, 0xffff0000, v68
	v_pk_mul_f32 v[106:107], v[82:83], v[84:85]
	v_lshlrev_b32_e32 v82, 16, v45
	v_and_b32_e32 v83, 0xffff0000, v45
	v_pk_add_f32 v[44:45], v[36:37], v[82:83]
	v_lshlrev_b32_e32 v36, 16, v49
	v_and_b32_e32 v37, 0xffff0000, v49
	v_pk_add_f32 v[48:49], v[44:45], v[36:37]
	v_lshlrev_b32_e32 v44, 16, v69
	v_and_b32_e32 v45, 0xffff0000, v69
	v_pk_fma_f32 v[68:69], v[32:33], v[48:49], v[82:83] op_sel_hi:[0,1,1] neg_lo:[0,0,1] neg_hi:[0,0,1]
	v_pk_mul_f32 v[68:69], v[68:69], v[44:45]
	v_pk_add_f32 v[44:45], v[108:109], 0 op_sel_hi:[1,0]
	v_lshlrev_b32_e32 v84, 16, v46
	v_pk_add_f32 v[44:45], v[44:45], v[110:111]
	v_and_b32_e32 v85, 0xffff0000, v46
	v_lshlrev_b32_e32 v112, 16, v39
	v_and_b32_e32 v113, 0xffff0000, v39
	v_pk_add_f32 v[38:39], v[44:45], v[84:85]
	v_lshlrev_b32_e32 v114, 16, v35
	v_and_b32_e32 v115, 0xffff0000, v35
	v_lshlrev_b32_e32 v34, 16, v50
	v_and_b32_e32 v35, 0xffff0000, v50
	v_pk_add_f32 v[116:117], v[38:39], v[34:35]
	v_lshlrev_b32_e32 v38, 16, v70
	v_and_b32_e32 v39, 0xffff0000, v70
	v_pk_fma_f32 v[44:45], v[32:33], v[116:117], v[84:85] op_sel_hi:[0,1,1] neg_lo:[0,0,1] neg_hi:[0,0,1]
	v_lshlrev_b32_e32 v86, 16, v47
	v_and_b32_e32 v87, 0xffff0000, v47
	v_pk_mul_f32 v[46:47], v[44:45], v[38:39]
	v_pk_add_f32 v[44:45], v[112:113], 0 op_sel_hi:[1,0]
	v_lshlrev_b32_e32 v38, 16, v51
	v_pk_add_f32 v[44:45], v[44:45], v[114:115]
	v_and_b32_e32 v39, 0xffff0000, v51
	v_pk_add_f32 v[44:45], v[44:45], v[86:87]
	v_cvt_pk_bf16_f32 v46, v46, v47
	v_pk_add_f32 v[118:119], v[44:45], v[38:39]
	v_lshlrev_b32_e32 v44, 16, v71
	v_and_b32_e32 v45, 0xffff0000, v71
	v_pk_fma_f32 v[32:33], v[32:33], v[118:119], v[86:87] op_sel_hi:[0,1,1] neg_lo:[0,0,1] neg_hi:[0,0,1]
	v_pk_mul_f32 v[50:51], v[32:33], v[44:45]
	v_mov_b64_e32 v[32:33], s[38:39]
	v_mad_i64_i32 v[44:45], s[6:7], v204, s34, v[32:33]
	v_lshl_add_u64 v[70:71], v[44:45], 0, v[154:155]
	v_min_u32_e32 v44, s2, v95
	v_sub_u32_e64 v45, v78, 2 clamp
	v_sub_u32_e32 v44, v44, v45
	v_cvt_f32_i32_e32 v78, v44
	v_cvt_pk_bf16_f32 v45, v68, v69
	v_cvt_pk_bf16_f32 v44, v106, v107
	v_cvt_pk_bf16_f32 v47, v50, v51
	v_div_scale_f32 v68, s[6:7], v78, v78, 1.0
	v_rcp_f32_e32 v69, v68
	global_store_dwordx4 v[70:71], v[44:47], off offset:2048 nt
	v_and_b32_e32 v79, 0xffff0000, v28
	v_lshlrev_b32_e32 v70, 16, v29
	v_fma_f32 v44, -v68, v69, 1.0
	v_fmac_f32_e32 v69, v44, v69
	v_div_scale_f32 v44, vcc, 1.0, v78, 1.0
	v_mul_f32_e32 v45, v44, v69
	v_fma_f32 v46, -v68, v45, v44
	v_fmac_f32_e32 v45, v46, v69
	v_fma_f32 v44, -v68, v45, v44
	v_div_fmas_f32 v44, v44, v69, v45
	v_div_fixup_f32 v44, v44, v78, 1.0
	v_lshlrev_b32_e32 v78, 16, v28
	v_pk_add_f32 v[46:47], v[78:79], v[88:89] neg_lo:[0,1] neg_hi:[0,1]
	v_and_b32_e32 v71, 0xffff0000, v29
	v_pk_add_f32 v[46:47], v[104:105], v[46:47]
	v_pk_add_f32 v[28:29], v[70:71], v[102:103] neg_lo:[0,1] neg_hi:[0,1]
	s_waitcnt vmcnt(7)
	v_lshlrev_b32_e32 v50, 16, v98
	v_and_b32_e32 v51, 0xffff0000, v98
	v_pk_fma_f32 v[68:69], v[44:45], v[46:47], v[72:73] op_sel_hi:[0,1,1] neg_lo:[0,0,1] neg_hi:[0,0,1]
	v_pk_add_f32 v[102:103], v[48:49], v[28:29]
	v_pk_mul_f32 v[88:89], v[68:69], v[50:51]
	v_lshlrev_b32_e32 v28, 16, v99
	v_and_b32_e32 v29, 0xffff0000, v99
	v_pk_fma_f32 v[48:49], v[44:45], v[102:103], v[36:37] op_sel_hi:[0,1,1] neg_lo:[0,0,1] neg_hi:[0,0,1]
	v_lshlrev_b32_e32 v68, 16, v30
	v_and_b32_e32 v69, 0xffff0000, v30
	v_pk_mul_f32 v[48:49], v[48:49], v[28:29]
	v_pk_add_f32 v[28:29], v[68:69], v[108:109] neg_lo:[0,1] neg_hi:[0,1]
	s_nop 0
	v_pk_add_f32 v[98:99], v[116:117], v[28:29]
	v_lshlrev_b32_e32 v28, 16, v100
	v_and_b32_e32 v29, 0xffff0000, v100
	v_pk_fma_f32 v[50:51], v[44:45], v[98:99], v[34:35] op_sel_hi:[0,1,1] neg_lo:[0,0,1] neg_hi:[0,0,1]
	v_pk_mul_f32 v[104:105], v[50:51], v[28:29]
	v_lshlrev_b32_e32 v50, 16, v31
	v_and_b32_e32 v51, 0xffff0000, v31
	v_pk_add_f32 v[28:29], v[50:51], v[112:113] neg_lo:[0,1] neg_hi:[0,1]
	s_nop 0
	v_pk_add_f32 v[106:107], v[118:119], v[28:29]
	v_lshlrev_b32_e32 v28, 16, v101
	v_and_b32_e32 v29, 0xffff0000, v101
	v_pk_fma_f32 v[30:31], v[44:45], v[106:107], v[38:39] op_sel_hi:[0,1,1] neg_lo:[0,0,1] neg_hi:[0,0,1]
	v_pk_mul_f32 v[44:45], v[30:31], v[28:29]
	v_or_b32_e32 v28, 1, v204
	v_mad_i64_i32 v[28:29], s[6:7], v28, s34, v[32:33]
	v_lshl_add_u64 v[100:101], v[28:29], 0, v[154:155]
	v_min_u32_e32 v28, s2, v94
	v_sub_u32_e32 v28, v28, v96
	v_add_u32_e32 v28, 2, v28
	v_cvt_f32_i32_e32 v96, v28
	v_cvt_pk_bf16_f32 v29, v48, v49
	v_cvt_pk_bf16_f32 v28, v88, v89
	v_cvt_pk_bf16_f32 v30, v104, v105
	v_div_scale_f32 v48, s[6:7], v96, v96, 1.0
	v_rcp_f32_e32 v49, v48
	v_cvt_pk_bf16_f32 v31, v44, v45
	global_store_dwordx4 v[100:101], v[28:31], off offset:2048 nt
	s_nop 1
	v_fma_f32 v28, -v48, v49, 1.0
	v_fmac_f32_e32 v49, v28, v49
	v_div_scale_f32 v28, vcc, 1.0, v96, 1.0
	v_mul_f32_e32 v29, v28, v49
	v_fma_f32 v30, -v48, v29, v28
	v_fmac_f32_e32 v29, v30, v49
	v_fma_f32 v28, -v48, v29, v28
	v_div_fmas_f32 v28, v28, v49, v29
	v_lshlrev_b32_e32 v48, 16, v24
	v_and_b32_e32 v49, 0xffff0000, v24
	v_pk_add_f32 v[30:31], v[48:49], v[76:77] neg_lo:[0,1] neg_hi:[0,1]
	v_div_fixup_f32 v28, v28, v96, 1.0
	v_pk_add_f32 v[76:77], v[46:47], v[30:31]
	v_lshlrev_b32_e32 v46, 16, v25
	v_and_b32_e32 v47, 0xffff0000, v25
	v_pk_add_f32 v[24:25], v[46:47], v[80:81] neg_lo:[0,1] neg_hi:[0,1]
	s_waitcnt vmcnt(7)
	v_lshlrev_b32_e32 v30, 16, v64
	v_and_b32_e32 v31, 0xffff0000, v64
	v_pk_fma_f32 v[44:45], v[28:29], v[76:77], v[78:79] op_sel_hi:[0,1,1] neg_lo:[0,0,1] neg_hi:[0,0,1]
	v_pk_add_f32 v[80:81], v[102:103], v[24:25]
	v_pk_mul_f32 v[88:89], v[44:45], v[30:31]
	v_lshlrev_b32_e32 v24, 16, v65
	v_and_b32_e32 v25, 0xffff0000, v65
	v_pk_fma_f32 v[30:31], v[28:29], v[80:81], v[70:71] op_sel_hi:[0,1,1] neg_lo:[0,0,1] neg_hi:[0,0,1]
	v_lshlrev_b32_e32 v44, 16, v26
	v_and_b32_e32 v45, 0xffff0000, v26
	v_pk_mul_f32 v[64:65], v[30:31], v[24:25]
	v_pk_add_f32 v[24:25], v[44:45], v[110:111] neg_lo:[0,1] neg_hi:[0,1]
	s_nop 0
	v_pk_add_f32 v[96:97], v[98:99], v[24:25]
	v_lshlrev_b32_e32 v24, 16, v66
	v_and_b32_e32 v25, 0xffff0000, v66
	v_pk_fma_f32 v[30:31], v[28:29], v[96:97], v[68:69] op_sel_hi:[0,1,1] neg_lo:[0,0,1] neg_hi:[0,0,1]
	v_pk_mul_f32 v[98:99], v[30:31], v[24:25]
	v_lshlrev_b32_e32 v30, 16, v27
	v_and_b32_e32 v31, 0xffff0000, v27
	v_pk_add_f32 v[24:25], v[30:31], v[114:115] neg_lo:[0,1] neg_hi:[0,1]
	s_nop 0
	v_pk_add_f32 v[100:101], v[106:107], v[24:25]
	v_lshlrev_b32_e32 v24, 16, v67
	v_and_b32_e32 v25, 0xffff0000, v67
	v_pk_fma_f32 v[26:27], v[28:29], v[100:101], v[50:51] op_sel_hi:[0,1,1] neg_lo:[0,0,1] neg_hi:[0,0,1]
	v_pk_mul_f32 v[28:29], v[26:27], v[24:25]
	v_or_b32_e32 v24, 2, v204
	v_mad_i64_i32 v[24:25], s[6:7], v24, s34, v[32:33]
	v_lshl_add_u64 v[66:67], v[24:25], 0, v[154:155]
	v_min_u32_e32 v24, s2, v92
	v_sub_u32_e32 v24, v24, v95
	v_add_u32_e32 v24, 2, v24
	v_cvt_f32_i32_e32 v95, v24
	v_cvt_pk_bf16_f32 v25, v64, v65
	v_cvt_pk_bf16_f32 v24, v88, v89
	v_cvt_pk_bf16_f32 v26, v98, v99
	v_div_scale_f32 v64, s[6:7], v95, v95, 1.0
	v_rcp_f32_e32 v65, v64
	v_cvt_pk_bf16_f32 v27, v28, v29
	global_store_dwordx4 v[66:67], v[24:27], off offset:2048 nt
	v_lshlrev_b32_e32 v28, 16, v16
	v_and_b32_e32 v29, 0xffff0000, v16
	v_fma_f32 v24, -v64, v65, 1.0
	v_fmac_f32_e32 v65, v24, v65
	v_div_scale_f32 v24, vcc, 1.0, v95, 1.0
	v_mul_f32_e32 v25, v24, v65
	v_fma_f32 v26, -v64, v25, v24
	v_fmac_f32_e32 v25, v26, v65
	v_fma_f32 v24, -v64, v25, v24
	v_div_fmas_f32 v24, v24, v65, v25
	v_div_fixup_f32 v64, v24, v95, 1.0
	v_pk_add_f32 v[24:25], v[28:29], v[74:75] neg_lo:[0,1] neg_hi:[0,1]
	s_nop 0
	v_pk_add_f32 v[66:67], v[76:77], v[24:25]
	s_waitcnt vmcnt(7)
	v_lshlrev_b32_e32 v24, 16, v60
	v_and_b32_e32 v25, 0xffff0000, v60
	v_pk_fma_f32 v[26:27], v[64:65], v[66:67], v[48:49] op_sel_hi:[0,1,1] neg_lo:[0,0,1] neg_hi:[0,0,1]
	v_pk_mul_f32 v[74:75], v[26:27], v[24:25]
	v_lshlrev_b32_e32 v26, 16, v17
	v_and_b32_e32 v27, 0xffff0000, v17
	v_pk_add_f32 v[16:17], v[26:27], v[82:83] neg_lo:[0,1] neg_hi:[0,1]
	s_nop 0
	v_pk_add_f32 v[76:77], v[80:81], v[16:17]
	v_lshlrev_b32_e32 v16, 16, v61
	v_and_b32_e32 v17, 0xffff0000, v61
	v_pk_fma_f32 v[24:25], v[64:65], v[76:77], v[46:47] op_sel_hi:[0,1,1] neg_lo:[0,0,1] neg_hi:[0,0,1]
	v_pk_mul_f32 v[80:81], v[24:25], v[16:17]
	v_lshlrev_b32_e32 v24, 16, v18
	v_and_b32_e32 v25, 0xffff0000, v18
	v_pk_add_f32 v[16:17], v[24:25], v[84:85] neg_lo:[0,1] neg_hi:[0,1]
	s_nop 0
	v_pk_add_f32 v[82:83], v[96:97], v[16:17]
	v_lshlrev_b32_e32 v16, 16, v62
	v_and_b32_e32 v17, 0xffff0000, v62
	v_pk_fma_f32 v[60:61], v[64:65], v[82:83], v[44:45] op_sel_hi:[0,1,1] neg_lo:[0,0,1] neg_hi:[0,0,1]
	v_pk_mul_f32 v[84:85], v[60:61], v[16:17]
	v_lshlrev_b32_e32 v16, 16, v19
	v_and_b32_e32 v17, 0xffff0000, v19
	v_pk_add_f32 v[18:19], v[16:17], v[86:87] neg_lo:[0,1] neg_hi:[0,1]
	v_lshlrev_b32_e32 v60, 16, v63
	v_pk_add_f32 v[18:19], v[100:101], v[18:19]
	v_and_b32_e32 v61, 0xffff0000, v63
	v_pk_fma_f32 v[62:63], v[64:65], v[18:19], v[30:31] op_sel_hi:[0,1,1] neg_lo:[0,0,1] neg_hi:[0,0,1]
	v_pk_mul_f32 v[64:65], v[62:63], v[60:61]
	v_or_b32_e32 v60, 3, v204
	v_mad_i64_i32 v[60:61], s[6:7], v60, s34, v[32:33]
	v_lshl_add_u64 v[86:87], v[60:61], 0, v[154:155]
	v_min_u32_e32 v60, s2, v91
	v_sub_u32_e32 v60, v60, v94
	v_add_u32_e32 v60, 2, v60
	v_cvt_f32_i32_e32 v88, v60
	v_cvt_pk_bf16_f32 v60, v74, v75
	v_cvt_pk_bf16_f32 v61, v80, v81
	v_cvt_pk_bf16_f32 v62, v84, v85
	v_div_scale_f32 v74, s[6:7], v88, v88, 1.0
	v_rcp_f32_e32 v75, v74
	v_cvt_pk_bf16_f32 v63, v64, v65
	global_store_dwordx4 v[86:87], v[60:63], off offset:2048 nt
	v_lshlrev_b32_e32 v80, 16, v15
	v_and_b32_e32 v81, 0xffff0000, v15
	v_fma_f32 v60, -v74, v75, 1.0
	v_fmac_f32_e32 v75, v60, v75
	v_div_scale_f32 v60, vcc, 1.0, v88, 1.0
	v_mul_f32_e32 v61, v60, v75
	v_fma_f32 v62, -v74, v61, v60
	v_fmac_f32_e32 v61, v62, v75
	v_fma_f32 v60, -v74, v61, v60
	v_lshlrev_b32_e32 v62, 16, v12
	v_and_b32_e32 v63, 0xffff0000, v12
	v_div_fmas_f32 v60, v60, v75, v61
	v_pk_add_f32 v[64:65], v[62:63], v[72:73] neg_lo:[0,1] neg_hi:[0,1]
	v_div_fixup_f32 v60, v60, v88, 1.0
	v_pk_add_f32 v[64:65], v[66:67], v[64:65]
	s_waitcnt vmcnt(7)
	v_lshlrev_b32_e32 v66, 16, v56
	v_and_b32_e32 v67, 0xffff0000, v56
	v_pk_fma_f32 v[72:73], v[60:61], v[64:65], v[28:29] op_sel_hi:[0,1,1] neg_lo:[0,0,1] neg_hi:[0,0,1]
	v_pk_mul_f32 v[66:67], v[72:73], v[66:67]
	v_lshlrev_b32_e32 v72, 16, v13
	v_and_b32_e32 v73, 0xffff0000, v13
	v_pk_add_f32 v[12:13], v[72:73], v[36:37] neg_lo:[0,1] neg_hi:[0,1]
	v_lshlrev_b32_e32 v74, 16, v14
	v_pk_add_f32 v[36:37], v[76:77], v[12:13]
	v_lshlrev_b32_e32 v12, 16, v57
	v_and_b32_e32 v13, 0xffff0000, v57
	v_pk_fma_f32 v[56:57], v[60:61], v[36:37], v[26:27] op_sel_hi:[0,1,1] neg_lo:[0,0,1] neg_hi:[0,0,1]
	v_and_b32_e32 v75, 0xffff0000, v14
	v_pk_mul_f32 v[56:57], v[56:57], v[12:13]
	v_pk_add_f32 v[12:13], v[74:75], v[34:35] neg_lo:[0,1] neg_hi:[0,1]
	s_nop 0
	v_pk_add_f32 v[34:35], v[82:83], v[12:13]
	v_lshlrev_b32_e32 v12, 16, v58
	v_and_b32_e32 v13, 0xffff0000, v58
	v_pk_fma_f32 v[76:77], v[60:61], v[34:35], v[24:25] op_sel_hi:[0,1,1] neg_lo:[0,0,1] neg_hi:[0,0,1]
	v_pk_mul_f32 v[76:77], v[76:77], v[12:13]
	v_pk_add_f32 v[12:13], v[80:81], v[38:39] neg_lo:[0,1] neg_hi:[0,1]
	s_nop 0
	v_pk_add_f32 v[18:19], v[18:19], v[12:13]
	v_lshlrev_b32_e32 v12, 16, v59
	v_and_b32_e32 v13, 0xffff0000, v59
	v_pk_fma_f32 v[14:15], v[60:61], v[18:19], v[16:17] op_sel_hi:[0,1,1] neg_lo:[0,0,1] neg_hi:[0,0,1]
	v_pk_mul_f32 v[38:39], v[14:15], v[12:13]
	v_or_b32_e32 v12, 4, v204
	v_mad_i64_i32 v[12:13], s[6:7], v12, s34, v[32:33]
	v_lshl_add_u64 v[58:59], v[12:13], 0, v[154:155]
	v_min_u32_e32 v12, s2, v90
	v_sub_u32_e32 v12, v12, v92
	v_add_u32_e32 v12, 2, v12
	v_cvt_f32_i32_e32 v60, v12
	v_cvt_pk_bf16_f32 v13, v56, v57
	v_cvt_pk_bf16_f32 v12, v66, v67
	v_cvt_pk_bf16_f32 v14, v76, v77
	v_div_scale_f32 v56, s[6:7], v60, v60, 1.0
	v_rcp_f32_e32 v57, v56
	v_cvt_pk_bf16_f32 v15, v38, v39
	global_store_dwordx4 v[58:59], v[12:15], off offset:2048 nt
	v_and_b32_e32 v61, 0xffff0000, v10
	s_nop 0
	v_fma_f32 v12, -v56, v57, 1.0
	v_fmac_f32_e32 v57, v12, v57
	v_div_scale_f32 v12, vcc, 1.0, v60, 1.0
	v_mul_f32_e32 v13, v12, v57
	v_fma_f32 v14, -v56, v13, v12
	v_fmac_f32_e32 v13, v14, v57
	v_fma_f32 v12, -v56, v13, v12
	v_lshlrev_b32_e32 v14, 16, v8
	v_and_b32_e32 v15, 0xffff0000, v8
	v_div_fmas_f32 v12, v12, v57, v13
	v_pk_add_f32 v[38:39], v[14:15], v[78:79] neg_lo:[0,1] neg_hi:[0,1]
	v_div_fixup_f32 v12, v12, v60, 1.0
	v_pk_add_f32 v[38:39], v[64:65], v[38:39]
	s_waitcnt vmcnt(7)
	v_lshlrev_b32_e32 v56, 16, v52
	v_and_b32_e32 v57, 0xffff0000, v52
	v_pk_fma_f32 v[58:59], v[12:13], v[38:39], v[62:63] op_sel_hi:[0,1,1] neg_lo:[0,0,1] neg_hi:[0,0,1]
	v_pk_mul_f32 v[56:57], v[58:59], v[56:57]
	v_lshlrev_b32_e32 v58, 16, v9
	v_and_b32_e32 v59, 0xffff0000, v9
	v_pk_add_f32 v[8:9], v[58:59], v[70:71] neg_lo:[0,1] neg_hi:[0,1]
	v_lshlrev_b32_e32 v60, 16, v10
	v_pk_add_f32 v[36:37], v[36:37], v[8:9]
	v_lshlrev_b32_e32 v8, 16, v53
	v_and_b32_e32 v9, 0xffff0000, v53
	v_pk_fma_f32 v[52:53], v[12:13], v[36:37], v[72:73] op_sel_hi:[0,1,1] neg_lo:[0,0,1] neg_hi:[0,0,1]
	v_pk_mul_f32 v[52:53], v[52:53], v[8:9]
	v_pk_add_f32 v[8:9], v[60:61], v[68:69] neg_lo:[0,1] neg_hi:[0,1]
	v_lshlrev_b32_e32 v64, 16, v11
	v_pk_add_f32 v[34:35], v[34:35], v[8:9]
	v_lshlrev_b32_e32 v8, 16, v54
	v_and_b32_e32 v9, 0xffff0000, v54
	v_pk_fma_f32 v[62:63], v[12:13], v[34:35], v[74:75] op_sel_hi:[0,1,1] neg_lo:[0,0,1] neg_hi:[0,0,1]
	v_and_b32_e32 v65, 0xffff0000, v11
	v_pk_mul_f32 v[62:63], v[62:63], v[8:9]
	v_pk_add_f32 v[8:9], v[64:65], v[50:51] neg_lo:[0,1] neg_hi:[0,1]
	s_nop 0
	v_pk_add_f32 v[18:19], v[18:19], v[8:9]
	v_lshlrev_b32_e32 v8, 16, v55
	v_and_b32_e32 v9, 0xffff0000, v55
	v_pk_fma_f32 v[10:11], v[12:13], v[18:19], v[80:81] op_sel_hi:[0,1,1] neg_lo:[0,0,1] neg_hi:[0,0,1]
	v_pk_mul_f32 v[12:13], v[10:11], v[8:9]
	v_or_b32_e32 v8, 5, v204
	v_mad_i64_i32 v[8:9], s[6:7], v8, s34, v[32:33]
	v_lshl_add_u64 v[50:51], v[8:9], 0, v[154:155]
	v_min_u32_e32 v8, s2, v93
	v_sub_u32_e32 v8, v8, v91
	v_add_u32_e32 v8, 2, v8
	v_cvt_f32_i32_e32 v54, v8
	v_cvt_pk_bf16_f32 v9, v52, v53
	v_cvt_pk_bf16_f32 v8, v56, v57
	v_cvt_pk_bf16_f32 v10, v62, v63
	v_div_scale_f32 v52, s[6:7], v54, v54, 1.0
	v_rcp_f32_e32 v53, v52
	v_cvt_pk_bf16_f32 v11, v12, v13
	global_store_dwordx4 v[50:51], v[8:11], off offset:2048 nt
	s_nop 1
	v_fma_f32 v8, -v52, v53, 1.0
	v_fmac_f32_e32 v53, v8, v53
	v_div_scale_f32 v8, vcc, 1.0, v54, 1.0
	v_mul_f32_e32 v9, v8, v53
	v_fma_f32 v10, -v52, v9, v8
	v_fmac_f32_e32 v9, v10, v53
	v_fma_f32 v8, -v52, v9, v8
	v_lshlrev_b32_e32 v10, 16, v4
	v_and_b32_e32 v11, 0xffff0000, v4
	v_div_fmas_f32 v8, v8, v53, v9
	v_pk_add_f32 v[12:13], v[10:11], v[48:49] neg_lo:[0,1] neg_hi:[0,1]
	v_div_fixup_f32 v8, v8, v54, 1.0
	v_pk_add_f32 v[12:13], v[38:39], v[12:13]
	s_waitcnt vmcnt(7)
	v_lshlrev_b32_e32 v38, 16, v40
	v_and_b32_e32 v39, 0xffff0000, v40
	v_pk_fma_f32 v[14:15], v[8:9], v[12:13], v[14:15] op_sel_hi:[0,1,1] neg_lo:[0,0,1] neg_hi:[0,0,1]
	v_pk_mul_f32 v[14:15], v[14:15], v[38:39]
	v_lshlrev_b32_e32 v38, 16, v5
	v_and_b32_e32 v39, 0xffff0000, v5
	v_pk_add_f32 v[4:5], v[38:39], v[46:47] neg_lo:[0,1] neg_hi:[0,1]
	v_lshlrev_b32_e32 v46, 16, v6
	v_pk_add_f32 v[36:37], v[36:37], v[4:5]
	v_lshlrev_b32_e32 v4, 16, v41
	v_and_b32_e32 v5, 0xffff0000, v41
	v_pk_fma_f32 v[40:41], v[8:9], v[36:37], v[58:59] op_sel_hi:[0,1,1] neg_lo:[0,0,1] neg_hi:[0,0,1]
	v_and_b32_e32 v47, 0xffff0000, v6
	v_pk_mul_f32 v[40:41], v[40:41], v[4:5]
	v_pk_add_f32 v[4:5], v[46:47], v[44:45] neg_lo:[0,1] neg_hi:[0,1]
	v_lshlrev_b32_e32 v48, 16, v7
	v_pk_add_f32 v[34:35], v[34:35], v[4:5]
	v_lshlrev_b32_e32 v4, 16, v42
	v_and_b32_e32 v5, 0xffff0000, v42
	v_pk_fma_f32 v[44:45], v[8:9], v[34:35], v[60:61] op_sel_hi:[0,1,1] neg_lo:[0,0,1] neg_hi:[0,0,1]
	v_and_b32_e32 v49, 0xffff0000, v7
	v_pk_mul_f32 v[44:45], v[44:45], v[4:5]
	v_pk_add_f32 v[4:5], v[48:49], v[30:31] neg_lo:[0,1] neg_hi:[0,1]
	s_nop 0
	v_pk_add_f32 v[18:19], v[18:19], v[4:5]
	v_lshlrev_b32_e32 v4, 16, v43
	v_and_b32_e32 v5, 0xffff0000, v43
	v_pk_fma_f32 v[6:7], v[8:9], v[18:19], v[64:65] op_sel_hi:[0,1,1] neg_lo:[0,0,1] neg_hi:[0,0,1]
	v_pk_mul_f32 v[8:9], v[6:7], v[4:5]
	v_or_b32_e32 v4, 6, v204
	v_mad_i64_i32 v[4:5], s[6:7], v4, s34, v[32:33]
	v_lshl_add_u64 v[30:31], v[4:5], 0, v[154:155]
	v_add_u32_e32 v4, 9, v206
	v_min_u32_e32 v4, s2, v4
	v_sub_u32_e32 v4, v4, v90
	v_add_u32_e32 v4, 2, v4
	v_cvt_f32_i32_e32 v42, v4
	v_cvt_pk_bf16_f32 v4, v14, v15
	v_cvt_pk_bf16_f32 v5, v40, v41
	v_cvt_pk_bf16_f32 v6, v44, v45
	v_div_scale_f32 v14, s[6:7], v42, v42, 1.0
	v_rcp_f32_e32 v15, v14
	v_cvt_pk_bf16_f32 v7, v8, v9
	global_store_dwordx4 v[30:31], v[4:7], off offset:2048 nt
	s_waitcnt vmcnt(7)
	v_lshlrev_b32_e32 v8, 16, v20
	v_and_b32_e32 v9, 0xffff0000, v20
	v_fma_f32 v4, -v14, v15, 1.0
	v_fmac_f32_e32 v15, v4, v15
	v_div_scale_f32 v4, vcc, 1.0, v42, 1.0
	v_mul_f32_e32 v5, v4, v15
	v_fma_f32 v6, -v14, v5, v4
	v_fmac_f32_e32 v5, v6, v15
	v_fma_f32 v4, -v14, v5, v4
	v_lshlrev_b32_e32 v6, 16, v0
	v_and_b32_e32 v7, 0xffff0000, v0
	v_div_fmas_f32 v4, v4, v15, v5
	v_pk_add_f32 v[6:7], v[6:7], v[28:29] neg_lo:[0,1] neg_hi:[0,1]
	v_lshlrev_b32_e32 v0, 16, v1
	v_and_b32_e32 v1, 0xffff0000, v1
	v_div_fixup_f32 v4, v4, v42, 1.0
	v_pk_add_f32 v[6:7], v[12:13], v[6:7]
	v_pk_add_f32 v[0:1], v[0:1], v[26:27] neg_lo:[0,1] neg_hi:[0,1]
	v_pk_fma_f32 v[6:7], v[4:5], v[6:7], v[10:11] op_sel_hi:[0,1,1] neg_lo:[0,0,1] neg_hi:[0,0,1]
	v_pk_add_f32 v[0:1], v[36:37], v[0:1]
	v_pk_mul_f32 v[6:7], v[6:7], v[8:9]
	v_lshlrev_b32_e32 v8, 16, v21
	v_and_b32_e32 v9, 0xffff0000, v21
	v_pk_fma_f32 v[0:1], v[4:5], v[0:1], v[38:39] op_sel_hi:[0,1,1] neg_lo:[0,0,1] neg_hi:[0,0,1]
	v_pk_mul_f32 v[8:9], v[0:1], v[8:9]
	v_lshlrev_b32_e32 v0, 16, v2
	v_and_b32_e32 v1, 0xffff0000, v2
	v_pk_add_f32 v[0:1], v[0:1], v[24:25] neg_lo:[0,1] neg_hi:[0,1]
	v_lshlrev_b32_e32 v10, 16, v22
	v_pk_add_f32 v[0:1], v[34:35], v[0:1]
	v_and_b32_e32 v11, 0xffff0000, v22
	v_pk_fma_f32 v[0:1], v[4:5], v[0:1], v[46:47] op_sel_hi:[0,1,1] neg_lo:[0,0,1] neg_hi:[0,0,1]
	v_pk_mul_f32 v[10:11], v[0:1], v[10:11]
	v_lshlrev_b32_e32 v0, 16, v3
	v_and_b32_e32 v1, 0xffff0000, v3
	v_pk_add_f32 v[0:1], v[0:1], v[16:17] neg_lo:[0,1] neg_hi:[0,1]
	v_lshlrev_b32_e32 v2, 16, v23
	v_pk_add_f32 v[0:1], v[18:19], v[0:1]
	v_and_b32_e32 v3, 0xffff0000, v23
	v_pk_fma_f32 v[0:1], v[4:5], v[0:1], v[48:49] op_sel_hi:[0,1,1] neg_lo:[0,0,1] neg_hi:[0,0,1]
	v_pk_mul_f32 v[4:5], v[0:1], v[2:3]
	v_or_b32_e32 v0, 7, v204
	v_mad_i64_i32 v[0:1], s[6:7], v0, s34, v[32:33]
	v_lshl_add_u64 v[12:13], v[0:1], 0, v[154:155]
	v_cvt_pk_bf16_f32 v0, v6, v7
	v_cvt_pk_bf16_f32 v1, v8, v9
	v_cvt_pk_bf16_f32 v2, v10, v11
	v_cvt_pk_bf16_f32 v3, v4, v5
	global_store_dwordx4 v[12:13], v[0:3], off offset:2048 nt

.LBB0_251:
	s_or_b64 exec, exec, s[0:1]
	v_add_co_u32_e32 v8, vcc, 0x2000, v126
	s_waitcnt vmcnt(1)
	v_lshlrev_b32_e32 v158, 16, v56
	v_addc_co_u32_e32 v9, vcc, 0, v127, vcc
	global_load_dwordx4 v[120:123], v[126:127], off offset:2048
	global_load_dwordx4 v[100:103], v[8:9], off offset:2176
	v_and_b32_e32 v159, 0xffff0000, v56
	v_pk_add_f32 v[128:129], v[158:159], 0 op_sel_hi:[1,0]
	v_lshlrev_b32_e32 v146, 16, v52
	v_and_b32_e32 v147, 0xffff0000, v52
	v_pk_add_f32 v[128:129], v[128:129], v[146:147]
	v_lshlrev_b32_e32 v138, 16, v76
	v_and_b32_e32 v139, 0xffff0000, v76
	v_pk_add_f32 v[128:129], v[128:129], v[138:139]
	v_lshlrev_b32_e32 v134, 16, v72
	v_and_b32_e32 v135, 0xffff0000, v72
	v_pk_add_f32 v[128:129], v[128:129], v[134:135]
	v_lshlrev_b32_e32 v132, 16, v92
	v_and_b32_e32 v133, 0xffff0000, v92
	v_pk_add_f32 v[128:129], v[128:129], v[132:133]
	v_lshlrev_b32_e32 v130, 16, v88
	v_and_b32_e32 v131, 0xffff0000, v88
	v_pk_add_f32 v[136:137], v[128:129], v[130:131]
	v_lshlrev_b32_e32 v128, 16, v108
	v_and_b32_e32 v129, 0xffff0000, v108
	v_lshlrev_b32_e32 v164, 16, v57
	v_and_b32_e32 v165, 0xffff0000, v57
	v_pk_add_f32 v[136:137], v[136:137], v[128:129]
	v_lshlrev_b32_e32 v140, 16, v104
	v_and_b32_e32 v141, 0xffff0000, v104
	v_pk_add_f32 v[56:57], v[164:165], 0 op_sel_hi:[1,0]
	v_lshlrev_b32_e32 v148, 16, v53
	v_and_b32_e32 v149, 0xffff0000, v53
	v_pk_add_f32 v[184:185], v[136:137], v[140:141]
	v_pk_add_f32 v[52:53], v[56:57], v[148:149]
	v_lshlrev_b32_e32 v140, 16, v77
	v_and_b32_e32 v141, 0xffff0000, v77
	v_pk_add_f32 v[52:53], v[52:53], v[140:141]
	v_lshlrev_b32_e32 v136, 16, v73
	v_and_b32_e32 v137, 0xffff0000, v73
	v_pk_add_f32 v[52:53], v[52:53], v[136:137]
	v_lshlrev_b32_e32 v92, 16, v93
	v_and_b32_e32 v93, 0xffff0000, v93
	v_pk_add_f32 v[52:53], v[52:53], v[92:93]
	v_lshlrev_b32_e32 v72, 16, v89
	v_and_b32_e32 v73, 0xffff0000, v89
	v_pk_add_f32 v[56:57], v[52:53], v[72:73]
	v_lshlrev_b32_e32 v52, 16, v109
	v_and_b32_e32 v53, 0xffff0000, v109
	v_pk_add_f32 v[56:57], v[56:57], v[52:53]
	v_lshlrev_b32_e32 v76, 16, v105
	v_and_b32_e32 v77, 0xffff0000, v105
	v_lshlrev_b32_e32 v170, 16, v58
	v_and_b32_e32 v171, 0xffff0000, v58
	v_pk_add_f32 v[190:191], v[56:57], v[76:77]
	v_pk_add_f32 v[56:57], v[170:171], 0 op_sel_hi:[1,0]
	v_lshlrev_b32_e32 v150, 16, v54
	v_and_b32_e32 v151, 0xffff0000, v54
	v_pk_add_f32 v[56:57], v[56:57], v[150:151]
	v_lshlrev_b32_e32 v142, 16, v78
	v_and_b32_e32 v143, 0xffff0000, v78
	v_pk_add_f32 v[56:57], v[56:57], v[142:143]
	v_lshlrev_b32_e32 v104, 16, v74
	v_and_b32_e32 v105, 0xffff0000, v74
	v_pk_add_f32 v[56:57], v[56:57], v[104:105]
	v_lshlrev_b32_e32 v88, 16, v94
	v_and_b32_e32 v89, 0xffff0000, v94
	v_pk_add_f32 v[56:57], v[56:57], v[88:89]
	v_lshlrev_b32_e32 v76, 16, v90
	v_and_b32_e32 v77, 0xffff0000, v90
	v_pk_add_f32 v[108:109], v[56:57], v[76:77]
	v_lshlrev_b32_e32 v56, 16, v110
	v_and_b32_e32 v57, 0xffff0000, v110
	v_lshlrev_b32_e32 v172, 16, v59
	v_and_b32_e32 v173, 0xffff0000, v59
	v_pk_add_f32 v[108:109], v[108:109], v[56:57]
	v_lshlrev_b32_e32 v144, 16, v106
	v_and_b32_e32 v145, 0xffff0000, v106
	v_pk_add_f32 v[58:59], v[172:173], 0 op_sel_hi:[1,0]
	v_lshlrev_b32_e32 v156, 16, v55
	v_and_b32_e32 v157, 0xffff0000, v55
	v_pk_add_f32 v[168:169], v[108:109], v[144:145]
	v_pk_add_f32 v[54:55], v[58:59], v[156:157]
	v_lshlrev_b32_e32 v144, 16, v79
	v_and_b32_e32 v145, 0xffff0000, v79
	v_pk_add_f32 v[54:55], v[54:55], v[144:145]
	v_lshlrev_b32_e32 v108, 16, v75
	v_and_b32_e32 v109, 0xffff0000, v75
	v_pk_add_f32 v[54:55], v[54:55], v[108:109]
	v_lshlrev_b32_e32 v78, 16, v95
	v_and_b32_e32 v79, 0xffff0000, v95
	v_pk_add_f32 v[54:55], v[54:55], v[78:79]
	v_lshlrev_b32_e32 v58, 16, v91
	v_and_b32_e32 v59, 0xffff0000, v91
	v_pk_add_f32 v[74:75], v[54:55], v[58:59]
	v_lshlrev_b32_e32 v54, 16, v111
	v_and_b32_e32 v55, 0xffff0000, v111
	v_pk_add_f32 v[74:75], v[74:75], v[54:55]
	v_lshlrev_b32_e32 v90, 16, v107
	v_and_b32_e32 v91, 0xffff0000, v107
	v_add_co_u32_e32 v8, vcc, 0x4000, v126
	v_pk_add_f32 v[176:177], v[74:75], v[90:91]
	v_min_u32_e32 v74, s2, v160
	v_sub_u32_e64 v75, v206, 8 clamp
	v_addc_co_u32_e32 v9, vcc, 0, v127, vcc
	v_sub_u32_e32 v74, v74, v75
	v_add_co_u32_e32 v10, vcc, 0x6000, v126
	v_cvt_f32_i32_e32 v74, v74
	s_nop 0
	v_addc_co_u32_e32 v11, vcc, 0, v127, vcc
	global_load_dwordx4 v[60:63], v[8:9], off offset:2304
	global_load_dwordx4 v[40:43], v[10:11], off offset:2432
	v_add_co_u32_e32 v8, vcc, 0x8000, v126
	v_div_scale_f32 v75, s[0:1], v74, v74, 1.0
	s_nop 0
	v_addc_co_u32_e32 v9, vcc, 0, v127, vcc
	v_add_co_u32_e32 v10, vcc, s11, v126
	v_rcp_f32_e32 v90, v75
	s_nop 0
	v_addc_co_u32_e32 v11, vcc, 0, v127, vcc
	global_load_dwordx4 v[36:39], v[8:9], off offset:2560
	global_load_dwordx4 v[28:31], v[10:11], off offset:2688
	v_add_co_u32_e32 v8, vcc, s12, v126
	v_fma_f32 v91, -v75, v90, 1.0
	s_nop 0
	v_addc_co_u32_e32 v9, vcc, 0, v127, vcc
	v_add_co_u32_e32 v10, vcc, s13, v126
	v_fmac_f32_e32 v90, v91, v90
	s_nop 0
	v_addc_co_u32_e32 v11, vcc, 0, v127, vcc
	v_div_scale_f32 v91, vcc, 1.0, v74, 1.0
	v_mul_f32_e32 v94, v91, v90
	v_fma_f32 v95, -v75, v94, v91
	v_fmac_f32_e32 v94, v95, v90
	v_fma_f32 v75, -v75, v94, v91
	v_div_fmas_f32 v75, v75, v90, v94
	s_waitcnt vmcnt(6)
	v_lshlrev_b32_e32 v110, 16, v48
	v_and_b32_e32 v111, 0xffff0000, v48
	v_lshlrev_b32_e32 v182, 16, v116
	v_and_b32_e32 v183, 0xffff0000, v116
	v_div_fixup_f32 v186, v75, v74, 1.0
	v_pk_add_f32 v[74:75], v[184:185], v[110:111]
	v_lshlrev_b32_e32 v166, 16, v112
	v_and_b32_e32 v167, 0xffff0000, v112
	v_pk_add_f32 v[74:75], v[74:75], v[182:183]
	v_lshlrev_b32_e32 v162, 16, v113
	v_and_b32_e32 v163, 0xffff0000, v113
	v_pk_add_f32 v[74:75], v[74:75], v[166:167]
	v_lshlrev_b32_e32 v112, 16, v68
	v_and_b32_e32 v113, 0xffff0000, v68
	v_pk_add_f32 v[74:75], v[74:75], v[112:113]
	v_lshlrev_b32_e32 v106, 16, v64
	v_and_b32_e32 v107, 0xffff0000, v64
	v_pk_add_f32 v[74:75], v[74:75], v[106:107]
	v_lshlrev_b32_e32 v94, 16, v84
	v_and_b32_e32 v95, 0xffff0000, v84
	v_pk_add_f32 v[74:75], v[74:75], v[94:95]
	v_lshlrev_b32_e32 v90, 16, v80
	v_and_b32_e32 v91, 0xffff0000, v80
	v_lshlrev_b32_e32 v180, 16, v117
	v_and_b32_e32 v181, 0xffff0000, v117
	v_pk_add_f32 v[116:117], v[74:75], v[90:91]
	v_lshlrev_b32_e32 v74, 16, v96
	v_and_b32_e32 v75, 0xffff0000, v96
	v_pk_add_f32 v[184:185], v[116:117], v[74:75]
	s_waitcnt vmcnt(5)
	v_lshlrev_b32_e32 v116, 16, v120
	v_and_b32_e32 v117, 0xffff0000, v120
	v_pk_fma_f32 v[110:111], v[186:187], v[184:185], v[110:111] op_sel_hi:[0,1,1] neg_lo:[0,0,1] neg_hi:[0,0,1]
	v_pk_mul_f32 v[188:189], v[110:111], v[116:117]
	v_lshlrev_b32_e32 v116, 16, v49
	v_and_b32_e32 v117, 0xffff0000, v49
	v_pk_add_f32 v[48:49], v[190:191], v[116:117]
	v_lshlrev_b32_e32 v178, 16, v118
	v_pk_add_f32 v[48:49], v[48:49], v[180:181]
	v_and_b32_e32 v179, 0xffff0000, v118
	v_lshlrev_b32_e32 v174, 16, v119
	v_and_b32_e32 v175, 0xffff0000, v119
	v_pk_add_f32 v[48:49], v[48:49], v[162:163]
	v_lshlrev_b32_e32 v118, 16, v69
	v_and_b32_e32 v119, 0xffff0000, v69
	v_pk_add_f32 v[48:49], v[48:49], v[118:119]
	v_lshlrev_b32_e32 v110, 16, v65
	v_and_b32_e32 v111, 0xffff0000, v65
	v_pk_add_f32 v[48:49], v[48:49], v[110:111]
	v_lshlrev_b32_e32 v84, 16, v85
	v_and_b32_e32 v85, 0xffff0000, v85
	v_pk_add_f32 v[48:49], v[48:49], v[84:85]
	v_lshlrev_b32_e32 v68, 16, v81
	v_and_b32_e32 v69, 0xffff0000, v81
	v_pk_add_f32 v[64:65], v[48:49], v[68:69]
	v_lshlrev_b32_e32 v48, 16, v97
	v_and_b32_e32 v49, 0xffff0000, v97
	v_pk_add_f32 v[190:191], v[64:65], v[48:49]
	v_lshlrev_b32_e32 v64, 16, v121
	v_and_b32_e32 v65, 0xffff0000, v121
	v_pk_fma_f32 v[80:81], v[186:187], v[190:191], v[116:117] op_sel_hi:[0,1,1] neg_lo:[0,0,1] neg_hi:[0,0,1]
	v_lshlrev_b32_e32 v120, 16, v50
	v_and_b32_e32 v121, 0xffff0000, v50
	v_pk_mul_f32 v[194:195], v[80:81], v[64:65]
	v_pk_add_f32 v[64:65], v[168:169], v[120:121]
	v_lshlrev_b32_e32 v160, 16, v114
	v_and_b32_e32 v161, 0xffff0000, v114
	v_pk_add_f32 v[64:65], v[64:65], v[178:179]
	v_lshlrev_b32_e32 v168, 16, v70
	v_pk_add_f32 v[64:65], v[64:65], v[160:161]
	v_and_b32_e32 v169, 0xffff0000, v70
	v_pk_add_f32 v[64:65], v[64:65], v[168:169]
	v_lshlrev_b32_e32 v116, 16, v66
	v_and_b32_e32 v117, 0xffff0000, v66
	v_pk_add_f32 v[64:65], v[64:65], v[116:117]
	v_lshlrev_b32_e32 v96, 16, v86
	v_and_b32_e32 v97, 0xffff0000, v86
	v_pk_add_f32 v[64:65], v[64:65], v[96:97]
	v_lshlrev_b32_e32 v80, 16, v82
	v_and_b32_e32 v81, 0xffff0000, v82
	v_lshlrev_b32_e32 v220, 16, v51
	v_and_b32_e32 v221, 0xffff0000, v51
	v_pk_add_f32 v[192:193], v[64:65], v[80:81]
	v_lshlrev_b32_e32 v64, 16, v98
	v_and_b32_e32 v65, 0xffff0000, v98
	v_pk_add_f32 v[50:51], v[176:177], v[220:221]
	v_lshlrev_b32_e32 v114, 16, v115
	v_and_b32_e32 v115, 0xffff0000, v115
	v_pk_add_f32 v[192:193], v[192:193], v[64:65]
	v_pk_add_f32 v[50:51], v[50:51], v[174:175]
	v_lshlrev_b32_e32 v196, 16, v122
	v_and_b32_e32 v197, 0xffff0000, v122
	v_pk_fma_f32 v[120:121], v[186:187], v[192:193], v[120:121] op_sel_hi:[0,1,1] neg_lo:[0,0,1] neg_hi:[0,0,1]
	v_pk_add_f32 v[50:51], v[50:51], v[114:115]
	v_lshlrev_b32_e32 v176, 16, v71
	v_and_b32_e32 v177, 0xffff0000, v71
	v_pk_mul_f32 v[196:197], v[120:121], v[196:197]
	v_pk_add_f32 v[50:51], v[50:51], v[176:177]
	v_lshlrev_b32_e32 v120, 16, v67
	v_and_b32_e32 v121, 0xffff0000, v67
	v_pk_add_f32 v[50:51], v[50:51], v[120:121]
	v_lshlrev_b32_e32 v86, 16, v87
	v_and_b32_e32 v87, 0xffff0000, v87
	v_pk_add_f32 v[50:51], v[50:51], v[86:87]
	v_lshlrev_b32_e32 v66, 16, v83
	v_and_b32_e32 v67, 0xffff0000, v83
	v_pk_add_f32 v[70:71], v[50:51], v[66:67]
	v_lshlrev_b32_e32 v50, 16, v99
	v_and_b32_e32 v51, 0xffff0000, v99
	v_pk_add_f32 v[82:83], v[70:71], v[50:51]
	v_sub_u32_e64 v216, v216, 8 clamp
	v_pk_fma_f32 v[98:99], v[186:187], v[82:83], v[220:221] op_sel_hi:[0,1,1] neg_lo:[0,0,1] neg_hi:[0,0,1]
	v_min_u32_e32 v186, s2, v219
	v_sub_u32_e32 v186, v186, v216
	v_cvt_f32_i32_e32 v186, v186
	v_cvt_pk_bf16_f32 v220, v188, v189
	v_lshlrev_b32_e32 v70, 16, v123
	v_and_b32_e32 v71, 0xffff0000, v123
	v_div_scale_f32 v188, s[0:1], v186, v186, 1.0
	v_rcp_f32_e32 v189, v188
	v_pk_mul_f32 v[98:99], v[98:99], v[70:71]
	v_mov_b64_e32 v[70:71], s[38:39]
	v_cvt_pk_bf16_f32 v223, v98, v99
	v_fma_f32 v98, -v188, v189, 1.0
	v_mad_i64_i32 v[122:123], s[0:1], v204, s34, v[70:71]
	v_fmac_f32_e32 v189, v98, v189
	v_div_scale_f32 v98, vcc, 1.0, v186, 1.0
	v_lshl_add_u64 v[122:123], v[122:123], 0, v[154:155]
	v_cvt_pk_bf16_f32 v221, v194, v195
	v_cvt_pk_bf16_f32 v222, v196, v197
	v_mul_f32_e32 v99, v98, v189
	global_load_dwordx4 v[16:19], v[8:9], off offset:2816
	s_nop 0
	global_load_dwordx4 v[8:11], v[10:11], off offset:2944
	s_nop 0
	global_store_dwordx4 v[122:123], v[220:223], off offset:2048 nt
	v_fma_f32 v122, -v188, v99, v98
	v_fmac_f32_e32 v99, v122, v189
	v_fma_f32 v98, -v188, v99, v98
	v_lshlrev_b32_e32 v122, 16, v44
	v_and_b32_e32 v123, 0xffff0000, v44
	v_lshlrev_b32_e32 v44, 16, v45
	v_and_b32_e32 v45, 0xffff0000, v45
	v_div_fmas_f32 v98, v98, v189, v99
	v_pk_add_f32 v[44:45], v[44:45], v[164:165] neg_lo:[0,1] neg_hi:[0,1]
	v_div_fixup_f32 v98, v98, v186, 1.0
	v_pk_add_f32 v[164:165], v[190:191], v[44:45]
	v_pk_add_f32 v[122:123], v[122:123], v[158:159] neg_lo:[0,1] neg_hi:[0,1]
	s_waitcnt vmcnt(7)
	v_lshlrev_b32_e32 v158, 16, v100
	v_and_b32_e32 v159, 0xffff0000, v100
	v_lshlrev_b32_e32 v44, 16, v101
	v_and_b32_e32 v45, 0xffff0000, v101
	v_pk_fma_f32 v[100:101], v[98:99], v[164:165], v[180:181] op_sel_hi:[0,1,1] neg_lo:[0,0,1] neg_hi:[0,0,1]
	v_pk_mul_f32 v[100:101], v[100:101], v[44:45]
	v_lshlrev_b32_e32 v44, 16, v46
	v_and_b32_e32 v45, 0xffff0000, v46
	v_pk_add_f32 v[44:45], v[44:45], v[170:171] neg_lo:[0,1] neg_hi:[0,1]
	v_pk_add_f32 v[122:123], v[184:185], v[122:123]
	v_pk_add_f32 v[170:171], v[192:193], v[44:45]
	v_lshlrev_b32_e32 v44, 16, v102
	v_and_b32_e32 v45, 0xffff0000, v102
	v_pk_fma_f32 v[178:179], v[98:99], v[170:171], v[178:179] op_sel_hi:[0,1,1] neg_lo:[0,0,1] neg_hi:[0,0,1]
	v_pk_mul_f32 v[178:179], v[178:179], v[44:45]
	v_lshlrev_b32_e32 v44, 16, v47
	v_and_b32_e32 v45, 0xffff0000, v47
	v_pk_add_f32 v[44:45], v[44:45], v[172:173] neg_lo:[0,1] neg_hi:[0,1]
	v_pk_fma_f32 v[182:183], v[98:99], v[122:123], v[182:183] op_sel_hi:[0,1,1] neg_lo:[0,0,1] neg_hi:[0,0,1]
	v_pk_add_f32 v[82:83], v[82:83], v[44:45]
	v_lshlrev_b32_e32 v44, 16, v103
	v_and_b32_e32 v45, 0xffff0000, v103
	v_pk_fma_f32 v[46:47], v[98:99], v[82:83], v[174:175] op_sel_hi:[0,1,1] neg_lo:[0,0,1] neg_hi:[0,0,1]
	v_pk_mul_f32 v[98:99], v[46:47], v[44:45]
	v_or_b32_e32 v44, 1, v204
	v_mad_i64_i32 v[44:45], s[0:1], v44, s34, v[70:71]
	v_lshl_add_u64 v[102:103], v[44:45], 0, v[154:155]
	v_min_u32_e32 v44, s2, v218
	v_sub_u32_e64 v45, v212, 8 clamp
	v_sub_u32_e32 v44, v44, v45
	v_cvt_f32_i32_e32 v172, v44
	v_cvt_pk_bf16_f32 v45, v100, v101
	v_pk_mul_f32 v[158:159], v[182:183], v[158:159]
	v_cvt_pk_bf16_f32 v46, v178, v179
	v_div_scale_f32 v100, s[0:1], v172, v172, 1.0
	v_rcp_f32_e32 v101, v100
	v_cvt_pk_bf16_f32 v44, v158, v159
	v_cvt_pk_bf16_f32 v47, v98, v99
	global_store_dwordx4 v[102:103], v[44:47], off offset:2048 nt
	s_waitcnt vmcnt(7)
	v_lshlrev_b32_e32 v98, 16, v60
	v_and_b32_e32 v99, 0xffff0000, v60
	v_fma_f32 v44, -v100, v101, 1.0
	v_fmac_f32_e32 v101, v44, v101
	v_div_scale_f32 v44, vcc, 1.0, v172, 1.0
	v_mul_f32_e32 v45, v44, v101
	v_fma_f32 v46, -v100, v45, v44
	v_fmac_f32_e32 v45, v46, v101
	v_fma_f32 v44, -v100, v45, v44
	v_lshlrev_b32_e32 v46, 16, v32
	v_and_b32_e32 v47, 0xffff0000, v32
	v_div_fmas_f32 v44, v44, v101, v45
	v_pk_add_f32 v[46:47], v[46:47], v[146:147] neg_lo:[0,1] neg_hi:[0,1]
	v_div_fixup_f32 v44, v44, v172, 1.0
	v_pk_add_f32 v[46:47], v[122:123], v[46:47]
	v_lshlrev_b32_e32 v32, 16, v33
	v_and_b32_e32 v33, 0xffff0000, v33
	v_pk_fma_f32 v[100:101], v[44:45], v[46:47], v[166:167] op_sel_hi:[0,1,1] neg_lo:[0,0,1] neg_hi:[0,0,1]
	v_pk_add_f32 v[32:33], v[32:33], v[148:149] neg_lo:[0,1] neg_hi:[0,1]
	v_pk_mul_f32 v[98:99], v[100:101], v[98:99]
	v_pk_add_f32 v[100:101], v[164:165], v[32:33]
	v_lshlrev_b32_e32 v32, 16, v61
	v_and_b32_e32 v33, 0xffff0000, v61
	v_pk_fma_f32 v[60:61], v[44:45], v[100:101], v[162:163] op_sel_hi:[0,1,1] neg_lo:[0,0,1] neg_hi:[0,0,1]
	v_pk_mul_f32 v[60:61], v[60:61], v[32:33]
	v_lshlrev_b32_e32 v32, 16, v34
	v_and_b32_e32 v33, 0xffff0000, v34
	v_pk_add_f32 v[32:33], v[32:33], v[150:151] neg_lo:[0,1] neg_hi:[0,1]
	s_nop 0
	v_pk_add_f32 v[102:103], v[170:171], v[32:33]
	v_lshlrev_b32_e32 v32, 16, v62
	v_and_b32_e32 v33, 0xffff0000, v62
	v_pk_fma_f32 v[122:123], v[44:45], v[102:103], v[160:161] op_sel_hi:[0,1,1] neg_lo:[0,0,1] neg_hi:[0,0,1]
	v_pk_mul_f32 v[122:123], v[122:123], v[32:33]
	v_lshlrev_b32_e32 v32, 16, v35
	v_and_b32_e32 v33, 0xffff0000, v35
	v_pk_add_f32 v[32:33], v[32:33], v[156:157] neg_lo:[0,1] neg_hi:[0,1]
	s_nop 0
	v_pk_add_f32 v[82:83], v[82:83], v[32:33]
	v_lshlrev_b32_e32 v32, 16, v63
	v_and_b32_e32 v33, 0xffff0000, v63
	v_pk_fma_f32 v[34:35], v[44:45], v[82:83], v[114:115] op_sel_hi:[0,1,1] neg_lo:[0,0,1] neg_hi:[0,0,1]
	v_pk_mul_f32 v[44:45], v[34:35], v[32:33]
	v_or_b32_e32 v32, 2, v204
	v_mad_i64_i32 v[32:33], s[0:1], v32, s34, v[70:71]
	v_lshl_add_u64 v[62:63], v[32:33], 0, v[154:155]
	v_min_u32_e32 v32, s2, v217
	v_sub_u32_e64 v33, v211, 8 clamp
	v_sub_u32_e32 v32, v32, v33
	v_cvt_f32_i32_e32 v114, v32
	v_cvt_pk_bf16_f32 v33, v60, v61
	v_cvt_pk_bf16_f32 v32, v98, v99
	v_cvt_pk_bf16_f32 v34, v122, v123
	v_div_scale_f32 v60, s[0:1], v114, v114, 1.0
	v_rcp_f32_e32 v61, v60
	v_cvt_pk_bf16_f32 v35, v44, v45
	global_store_dwordx4 v[62:63], v[32:35], off offset:2048 nt
	s_waitcnt vmcnt(7)
	v_lshlrev_b32_e32 v44, 16, v40
	v_and_b32_e32 v45, 0xffff0000, v40
	v_fma_f32 v32, -v60, v61, 1.0
	v_fmac_f32_e32 v61, v32, v61
	v_div_scale_f32 v32, vcc, 1.0, v114, 1.0
	v_mul_f32_e32 v33, v32, v61
	v_fma_f32 v34, -v60, v33, v32
	v_fmac_f32_e32 v33, v34, v61
	v_fma_f32 v32, -v60, v33, v32
	v_lshlrev_b32_e32 v34, 16, v24
	v_and_b32_e32 v35, 0xffff0000, v24
	v_div_fmas_f32 v32, v32, v61, v33
	v_pk_add_f32 v[34:35], v[34:35], v[138:139] neg_lo:[0,1] neg_hi:[0,1]
	v_div_fixup_f32 v32, v32, v114, 1.0
	v_pk_add_f32 v[34:35], v[46:47], v[34:35]
	v_lshlrev_b32_e32 v24, 16, v25
	v_and_b32_e32 v25, 0xffff0000, v25
	v_pk_fma_f32 v[46:47], v[32:33], v[34:35], v[112:113] op_sel_hi:[0,1,1] neg_lo:[0,0,1] neg_hi:[0,0,1]
	v_pk_add_f32 v[24:25], v[24:25], v[140:141] neg_lo:[0,1] neg_hi:[0,1]
	v_pk_mul_f32 v[44:45], v[46:47], v[44:45]
	v_pk_add_f32 v[46:47], v[100:101], v[24:25]
	v_lshlrev_b32_e32 v24, 16, v41
	v_and_b32_e32 v25, 0xffff0000, v41
	v_pk_fma_f32 v[40:41], v[32:33], v[46:47], v[118:119] op_sel_hi:[0,1,1] neg_lo:[0,0,1] neg_hi:[0,0,1]
	v_pk_mul_f32 v[40:41], v[40:41], v[24:25]
	v_lshlrev_b32_e32 v24, 16, v26
	v_and_b32_e32 v25, 0xffff0000, v26
	v_pk_add_f32 v[24:25], v[24:25], v[142:143] neg_lo:[0,1] neg_hi:[0,1]
	s_nop 0
	v_pk_add_f32 v[60:61], v[102:103], v[24:25]
	v_lshlrev_b32_e32 v24, 16, v42
	v_and_b32_e32 v25, 0xffff0000, v42
	v_pk_fma_f32 v[62:63], v[32:33], v[60:61], v[168:169] op_sel_hi:[0,1,1] neg_lo:[0,0,1] neg_hi:[0,0,1]
	v_pk_mul_f32 v[62:63], v[62:63], v[24:25]
	v_lshlrev_b32_e32 v24, 16, v27
	v_and_b32_e32 v25, 0xffff0000, v27
	v_pk_add_f32 v[24:25], v[24:25], v[144:145] neg_lo:[0,1] neg_hi:[0,1]
	s_nop 0
	v_pk_add_f32 v[82:83], v[82:83], v[24:25]
	v_lshlrev_b32_e32 v24, 16, v43
	v_and_b32_e32 v25, 0xffff0000, v43
	v_pk_fma_f32 v[26:27], v[32:33], v[82:83], v[176:177] op_sel_hi:[0,1,1] neg_lo:[0,0,1] neg_hi:[0,0,1]
	v_pk_mul_f32 v[32:33], v[26:27], v[24:25]
	v_or_b32_e32 v24, 3, v204
	v_mad_i64_i32 v[24:25], s[0:1], v24, s34, v[70:71]
	v_lshl_add_u64 v[42:43], v[24:25], 0, v[154:155]
	v_min_u32_e32 v24, s2, v215
	v_sub_u32_e64 v25, v210, 8 clamp
	v_sub_u32_e32 v24, v24, v25
	v_cvt_f32_i32_e32 v98, v24
	v_cvt_pk_bf16_f32 v25, v40, v41
	v_cvt_pk_bf16_f32 v24, v44, v45
	v_cvt_pk_bf16_f32 v26, v62, v63
	v_div_scale_f32 v40, s[0:1], v98, v98, 1.0
	v_rcp_f32_e32 v41, v40
	v_cvt_pk_bf16_f32 v27, v32, v33
	global_store_dwordx4 v[42:43], v[24:27], off offset:2048 nt
	s_waitcnt vmcnt(7)
	v_lshlrev_b32_e32 v32, 16, v36
	v_and_b32_e32 v33, 0xffff0000, v36
	v_fma_f32 v24, -v40, v41, 1.0
	v_fmac_f32_e32 v41, v24, v41
	v_div_scale_f32 v24, vcc, 1.0, v98, 1.0
	v_mul_f32_e32 v25, v24, v41
	v_fma_f32 v26, -v40, v25, v24
	v_fmac_f32_e32 v25, v26, v41
	v_fma_f32 v24, -v40, v25, v24
	v_lshlrev_b32_e32 v26, 16, v20
	v_and_b32_e32 v27, 0xffff0000, v20
	v_div_fmas_f32 v24, v24, v41, v25
	v_pk_add_f32 v[26:27], v[26:27], v[134:135] neg_lo:[0,1] neg_hi:[0,1]
	v_div_fixup_f32 v24, v24, v98, 1.0
	v_pk_add_f32 v[26:27], v[34:35], v[26:27]
	v_lshlrev_b32_e32 v20, 16, v21
	v_and_b32_e32 v21, 0xffff0000, v21
	v_pk_fma_f32 v[34:35], v[24:25], v[26:27], v[106:107] op_sel_hi:[0,1,1] neg_lo:[0,0,1] neg_hi:[0,0,1]
	v_pk_add_f32 v[20:21], v[20:21], v[136:137] neg_lo:[0,1] neg_hi:[0,1]
	v_pk_mul_f32 v[32:33], v[34:35], v[32:33]
	v_pk_add_f32 v[34:35], v[46:47], v[20:21]
	v_lshlrev_b32_e32 v20, 16, v37
	v_and_b32_e32 v21, 0xffff0000, v37
	v_pk_fma_f32 v[36:37], v[24:25], v[34:35], v[110:111] op_sel_hi:[0,1,1] neg_lo:[0,0,1] neg_hi:[0,0,1]
	v_pk_mul_f32 v[36:37], v[36:37], v[20:21]
	v_lshlrev_b32_e32 v20, 16, v22
	v_and_b32_e32 v21, 0xffff0000, v22
	v_pk_add_f32 v[20:21], v[20:21], v[104:105] neg_lo:[0,1] neg_hi:[0,1]
	s_nop 0
	v_pk_add_f32 v[40:41], v[60:61], v[20:21]
	v_lshlrev_b32_e32 v20, 16, v38
	v_and_b32_e32 v21, 0xffff0000, v38
	v_pk_fma_f32 v[42:43], v[24:25], v[40:41], v[116:117] op_sel_hi:[0,1,1] neg_lo:[0,0,1] neg_hi:[0,0,1]
	v_pk_mul_f32 v[42:43], v[42:43], v[20:21]
	v_lshlrev_b32_e32 v20, 16, v23
	v_and_b32_e32 v21, 0xffff0000, v23
	v_pk_add_f32 v[20:21], v[20:21], v[108:109] neg_lo:[0,1] neg_hi:[0,1]
	s_nop 0
	v_pk_add_f32 v[44:45], v[82:83], v[20:21]
	v_lshlrev_b32_e32 v20, 16, v39
	v_and_b32_e32 v21, 0xffff0000, v39
	v_pk_fma_f32 v[22:23], v[24:25], v[44:45], v[120:121] op_sel_hi:[0,1,1] neg_lo:[0,0,1] neg_hi:[0,0,1]
	v_pk_mul_f32 v[24:25], v[22:23], v[20:21]
	v_or_b32_e32 v20, 4, v204
	v_mad_i64_i32 v[20:21], s[0:1], v20, s34, v[70:71]
	v_lshl_add_u64 v[38:39], v[20:21], 0, v[154:155]
	v_min_u32_e32 v20, s2, v214
	v_sub_u32_e64 v21, v209, 8 clamp
	v_sub_u32_e32 v20, v20, v21
	v_cvt_f32_i32_e32 v46, v20
	v_cvt_pk_bf16_f32 v20, v32, v33
	v_cvt_pk_bf16_f32 v21, v36, v37
	v_cvt_pk_bf16_f32 v22, v42, v43
	v_div_scale_f32 v32, s[0:1], v46, v46, 1.0
	v_rcp_f32_e32 v33, v32
	v_cvt_pk_bf16_f32 v23, v24, v25
	global_store_dwordx4 v[38:39], v[20:23], off offset:2048 nt
	s_waitcnt vmcnt(7)
	v_lshlrev_b32_e32 v24, 16, v28
	v_and_b32_e32 v25, 0xffff0000, v28
	v_fma_f32 v20, -v32, v33, 1.0
	v_fmac_f32_e32 v33, v20, v33
	v_div_scale_f32 v20, vcc, 1.0, v46, 1.0
	v_mul_f32_e32 v21, v20, v33
	v_fma_f32 v22, -v32, v21, v20
	v_fmac_f32_e32 v21, v22, v33
	v_fma_f32 v20, -v32, v21, v20
	v_lshlrev_b32_e32 v22, 16, v12
	v_and_b32_e32 v23, 0xffff0000, v12
	v_div_fmas_f32 v20, v20, v33, v21
	v_pk_add_f32 v[22:23], v[22:23], v[132:133] neg_lo:[0,1] neg_hi:[0,1]
	v_div_fixup_f32 v20, v20, v46, 1.0
	v_pk_add_f32 v[22:23], v[26:27], v[22:23]
	v_lshlrev_b32_e32 v12, 16, v13
	v_and_b32_e32 v13, 0xffff0000, v13
	v_pk_fma_f32 v[26:27], v[20:21], v[22:23], v[94:95] op_sel_hi:[0,1,1] neg_lo:[0,0,1] neg_hi:[0,0,1]
	v_pk_add_f32 v[12:13], v[12:13], v[92:93] neg_lo:[0,1] neg_hi:[0,1]
	v_pk_mul_f32 v[24:25], v[26:27], v[24:25]
	v_pk_add_f32 v[26:27], v[34:35], v[12:13]
	v_lshlrev_b32_e32 v12, 16, v29
	v_and_b32_e32 v13, 0xffff0000, v29
	v_pk_fma_f32 v[28:29], v[20:21], v[26:27], v[84:85] op_sel_hi:[0,1,1] neg_lo:[0,0,1] neg_hi:[0,0,1]
	v_pk_mul_f32 v[28:29], v[28:29], v[12:13]
	v_lshlrev_b32_e32 v12, 16, v14
	v_and_b32_e32 v13, 0xffff0000, v14
	v_pk_add_f32 v[12:13], v[12:13], v[88:89] neg_lo:[0,1] neg_hi:[0,1]
	s_nop 0
	v_pk_add_f32 v[32:33], v[40:41], v[12:13]
	v_lshlrev_b32_e32 v12, 16, v30
	v_and_b32_e32 v13, 0xffff0000, v30
	v_pk_fma_f32 v[34:35], v[20:21], v[32:33], v[96:97] op_sel_hi:[0,1,1] neg_lo:[0,0,1] neg_hi:[0,0,1]
	v_pk_mul_f32 v[34:35], v[34:35], v[12:13]
	v_lshlrev_b32_e32 v12, 16, v15
	v_and_b32_e32 v13, 0xffff0000, v15
	v_pk_add_f32 v[12:13], v[12:13], v[78:79] neg_lo:[0,1] neg_hi:[0,1]
	s_nop 0
	v_pk_add_f32 v[36:37], v[44:45], v[12:13]
	v_lshlrev_b32_e32 v12, 16, v31
	v_and_b32_e32 v13, 0xffff0000, v31
	v_pk_fma_f32 v[14:15], v[20:21], v[36:37], v[86:87] op_sel_hi:[0,1,1] neg_lo:[0,0,1] neg_hi:[0,0,1]
	v_pk_mul_f32 v[20:21], v[14:15], v[12:13]
	v_or_b32_e32 v12, 5, v204
	v_mad_i64_i32 v[12:13], s[0:1], v12, s34, v[70:71]
	v_lshl_add_u64 v[30:31], v[12:13], 0, v[154:155]
	v_min_u32_e32 v12, s2, v213
	v_sub_u32_e64 v13, v208, 8 clamp
	v_sub_u32_e32 v12, v12, v13
	v_cvt_f32_i32_e32 v38, v12
	v_cvt_pk_bf16_f32 v12, v24, v25
	v_cvt_pk_bf16_f32 v13, v28, v29
	v_cvt_pk_bf16_f32 v14, v34, v35
	v_div_scale_f32 v24, s[0:1], v38, v38, 1.0
	v_rcp_f32_e32 v25, v24
	v_cvt_pk_bf16_f32 v15, v20, v21
	global_store_dwordx4 v[30:31], v[12:15], off offset:2048 nt
	s_waitcnt vmcnt(7)
	v_lshlrev_b32_e32 v20, 16, v16
	v_and_b32_e32 v21, 0xffff0000, v16
	v_fma_f32 v12, -v24, v25, 1.0
	v_fmac_f32_e32 v25, v12, v25
	v_div_scale_f32 v12, vcc, 1.0, v38, 1.0
	v_mul_f32_e32 v13, v12, v25
	v_fma_f32 v14, -v24, v13, v12
	v_fmac_f32_e32 v13, v14, v25
	v_fma_f32 v12, -v24, v13, v12
	v_lshlrev_b32_e32 v14, 16, v4
	v_and_b32_e32 v15, 0xffff0000, v4
	v_div_fmas_f32 v12, v12, v25, v13
	v_pk_add_f32 v[14:15], v[14:15], v[130:131] neg_lo:[0,1] neg_hi:[0,1]
	v_div_fixup_f32 v12, v12, v38, 1.0
	v_pk_add_f32 v[14:15], v[22:23], v[14:15]
	v_lshlrev_b32_e32 v4, 16, v5
	v_and_b32_e32 v5, 0xffff0000, v5
	v_pk_fma_f32 v[22:23], v[12:13], v[14:15], v[90:91] op_sel_hi:[0,1,1] neg_lo:[0,0,1] neg_hi:[0,0,1]
	v_pk_add_f32 v[4:5], v[4:5], v[72:73] neg_lo:[0,1] neg_hi:[0,1]
	v_pk_mul_f32 v[20:21], v[22:23], v[20:21]
	v_pk_add_f32 v[22:23], v[26:27], v[4:5]
	v_lshlrev_b32_e32 v4, 16, v17
	v_and_b32_e32 v5, 0xffff0000, v17
	v_pk_fma_f32 v[16:17], v[12:13], v[22:23], v[68:69] op_sel_hi:[0,1,1] neg_lo:[0,0,1] neg_hi:[0,0,1]
	v_pk_mul_f32 v[16:17], v[16:17], v[4:5]
	v_lshlrev_b32_e32 v4, 16, v6
	v_and_b32_e32 v5, 0xffff0000, v6
	v_pk_add_f32 v[4:5], v[4:5], v[76:77] neg_lo:[0,1] neg_hi:[0,1]
	s_nop 0
	v_pk_add_f32 v[24:25], v[32:33], v[4:5]
	v_lshlrev_b32_e32 v4, 16, v18
	v_and_b32_e32 v5, 0xffff0000, v18
	v_pk_fma_f32 v[26:27], v[12:13], v[24:25], v[80:81] op_sel_hi:[0,1,1] neg_lo:[0,0,1] neg_hi:[0,0,1]
	v_pk_mul_f32 v[26:27], v[26:27], v[4:5]
	v_lshlrev_b32_e32 v4, 16, v7
	v_and_b32_e32 v5, 0xffff0000, v7
	v_pk_add_f32 v[4:5], v[4:5], v[58:59] neg_lo:[0,1] neg_hi:[0,1]
	s_nop 0
	v_pk_add_f32 v[28:29], v[36:37], v[4:5]
	v_lshlrev_b32_e32 v4, 16, v19
	v_and_b32_e32 v5, 0xffff0000, v19
	v_pk_fma_f32 v[6:7], v[12:13], v[28:29], v[66:67] op_sel_hi:[0,1,1] neg_lo:[0,0,1] neg_hi:[0,0,1]
	v_pk_mul_f32 v[12:13], v[6:7], v[4:5]
	v_or_b32_e32 v4, 6, v204
	v_mad_i64_i32 v[4:5], s[0:1], v4, s34, v[70:71]
	v_lshl_add_u64 v[18:19], v[4:5], 0, v[154:155]
	v_add_u32_e32 v4, 15, v206
	v_min_u32_e32 v4, s2, v4
	v_sub_u32_e64 v5, v207, 8 clamp
	v_sub_u32_e32 v4, v4, v5
	v_cvt_f32_i32_e32 v30, v4
	v_cvt_pk_bf16_f32 v5, v16, v17
	v_cvt_pk_bf16_f32 v4, v20, v21
	v_cvt_pk_bf16_f32 v6, v26, v27
	v_div_scale_f32 v16, s[0:1], v30, v30, 1.0
	v_rcp_f32_e32 v17, v16
	v_cvt_pk_bf16_f32 v7, v12, v13
	global_store_dwordx4 v[18:19], v[4:7], off offset:2048 nt
	s_waitcnt vmcnt(7)
	v_lshlrev_b32_e32 v12, 16, v8
	v_and_b32_e32 v13, 0xffff0000, v8
	v_fma_f32 v4, -v16, v17, 1.0
	v_fmac_f32_e32 v17, v4, v17
	v_div_scale_f32 v4, vcc, 1.0, v30, 1.0
	v_mul_f32_e32 v5, v4, v17
	v_fma_f32 v6, -v16, v5, v4
	v_fmac_f32_e32 v5, v6, v17
	v_fma_f32 v4, -v16, v5, v4
	v_lshlrev_b32_e32 v6, 16, v0
	v_and_b32_e32 v7, 0xffff0000, v0
	v_lshlrev_b32_e32 v0, 16, v1
	v_and_b32_e32 v1, 0xffff0000, v1
	v_div_fmas_f32 v4, v4, v17, v5
	v_pk_add_f32 v[0:1], v[0:1], v[52:53] neg_lo:[0,1] neg_hi:[0,1]
	v_div_fixup_f32 v4, v4, v30, 1.0
	v_pk_add_f32 v[0:1], v[22:23], v[0:1]
	v_lshlrev_b32_e32 v8, 16, v9
	v_and_b32_e32 v9, 0xffff0000, v9
	v_pk_fma_f32 v[0:1], v[4:5], v[0:1], v[48:49] op_sel_hi:[0,1,1] neg_lo:[0,0,1] neg_hi:[0,0,1]
	v_pk_add_f32 v[6:7], v[6:7], v[128:129] neg_lo:[0,1] neg_hi:[0,1]
	v_pk_mul_f32 v[8:9], v[0:1], v[8:9]
	v_lshlrev_b32_e32 v0, 16, v2
	v_and_b32_e32 v1, 0xffff0000, v2
	v_pk_add_f32 v[6:7], v[14:15], v[6:7]
	v_pk_add_f32 v[0:1], v[0:1], v[56:57] neg_lo:[0,1] neg_hi:[0,1]
	v_pk_fma_f32 v[6:7], v[4:5], v[6:7], v[74:75] op_sel_hi:[0,1,1] neg_lo:[0,0,1] neg_hi:[0,0,1]
	v_pk_add_f32 v[0:1], v[24:25], v[0:1]
	v_pk_mul_f32 v[6:7], v[6:7], v[12:13]
	v_lshlrev_b32_e32 v12, 16, v10
	v_and_b32_e32 v13, 0xffff0000, v10
	v_pk_fma_f32 v[0:1], v[4:5], v[0:1], v[64:65] op_sel_hi:[0,1,1] neg_lo:[0,0,1] neg_hi:[0,0,1]
	v_pk_mul_f32 v[12:13], v[0:1], v[12:13]
	v_lshlrev_b32_e32 v0, 16, v3
	v_and_b32_e32 v1, 0xffff0000, v3
	v_pk_add_f32 v[0:1], v[0:1], v[54:55] neg_lo:[0,1] neg_hi:[0,1]
	v_lshlrev_b32_e32 v2, 16, v11
	v_pk_add_f32 v[0:1], v[28:29], v[0:1]
	v_and_b32_e32 v3, 0xffff0000, v11
	v_pk_fma_f32 v[0:1], v[4:5], v[0:1], v[50:51] op_sel_hi:[0,1,1] neg_lo:[0,0,1] neg_hi:[0,0,1]
	v_pk_mul_f32 v[4:5], v[0:1], v[2:3]
	v_or_b32_e32 v0, 7, v204
	v_mad_i64_i32 v[0:1], s[0:1], v0, s34, v[70:71]
	v_lshl_add_u64 v[10:11], v[0:1], 0, v[154:155]
	v_cvt_pk_bf16_f32 v0, v6, v7
	v_cvt_pk_bf16_f32 v1, v8, v9
	v_cvt_pk_bf16_f32 v2, v12, v13
	v_cvt_pk_bf16_f32 v3, v4, v5
	global_store_dwordx4 v[10:11], v[0:3], off offset:2048 nt

.LBB0_291:
	s_or_b64 exec, exec, s[0:1]
	global_load_dwordx4 v[68:71], v[126:127], off offset:2048
	v_add_co_u32_e32 v20, vcc, 0x2000, v126
	s_mov_b64 s[40:41], vcc
	v_min_u32_e32 v21, s2, v66
	v_sub_u32_e64 v23, v206, 1 clamp
	v_add_co_u32_e32 v22, vcc, 0x4000, v126
	s_mov_b64 s[42:43], vcc
	v_sub_u32_e32 v23, v21, v23
	v_addc_co_u32_e64 v21, vcc, 0, v127, s[40:41]
	global_load_dwordx4 v[72:75], v[20:21], off offset:2176
	v_add_co_u32_e32 v42, vcc, 0x6000, v126
	s_mov_b64 s[40:41], vcc
	v_cvt_f32_i32_e32 v67, v23
	v_addc_co_u32_e64 v23, vcc, 0, v127, s[42:43]
	v_add_co_u32_e32 v20, vcc, 0x8000, v126
	s_mov_b64 s[42:43], vcc
	v_addc_co_u32_e64 v43, vcc, 0, v127, s[40:41]
	global_load_dwordx4 v[54:57], v[22:23], off offset:2304
	global_load_dwordx4 v[50:53], v[42:43], off offset:2432
	s_waitcnt vmcnt(5)
	v_lshlrev_b32_e32 v76, 16, v34
	v_and_b32_e32 v77, 0xffff0000, v34
	s_waitcnt vmcnt(4)
	v_lshlrev_b32_e32 v58, 16, v38
	v_and_b32_e32 v59, 0xffff0000, v38
	v_pk_add_f32 v[32:33], v[76:77], 0 op_sel_hi:[1,0]
	v_div_scale_f32 v81, s[0:1], v67, v67, 1.0
	v_pk_add_f32 v[82:83], v[32:33], v[58:59]
	v_add_co_u32_e32 v32, vcc, s11, v126
	s_mov_b64 s[40:41], vcc
	v_addc_co_u32_e64 v21, vcc, 0, v127, s[42:43]
	v_rcp_f32_e32 v89, v81
	v_add_co_u32_e32 v22, vcc, s12, v126
	v_lshlrev_b32_e32 v78, 16, v35
	v_and_b32_e32 v79, 0xffff0000, v35
	s_mov_b64 s[42:43], vcc
	v_addc_co_u32_e64 v33, vcc, 0, v127, s[40:41]
	v_lshlrev_b32_e32 v38, 16, v39
	v_and_b32_e32 v39, 0xffff0000, v39
	v_pk_add_f32 v[34:35], v[78:79], 0 op_sel_hi:[1,0]
	v_add_co_u32_e32 v86, vcc, s13, v126
	v_addc_co_u32_e64 v23, s[42:43], 0, v127, s[42:43]
	v_pk_add_f32 v[84:85], v[34:35], v[38:39]
	global_load_dwordx4 v[46:49], v[20:21], off offset:2560
	global_load_dwordx4 v[42:45], v[32:33], off offset:2688
	v_addc_co_u32_e32 v87, vcc, 0, v127, vcc
	global_load_dwordx4 v[32:35], v[22:23], off offset:2816
	s_nop 0
	global_load_dwordx4 v[20:23], v[86:87], off offset:2944
	v_fma_f32 v86, -v81, v89, 1.0
	v_div_scale_f32 v88, s[40:41], 1.0, v67, 1.0
	v_fmac_f32_e32 v89, v86, v89
	v_mul_f32_e32 v86, v88, v89
	v_fma_f32 v87, -v81, v86, v88
	v_fmac_f32_e32 v86, v87, v89
	v_fma_f32 v81, -v81, v86, v88
	s_mov_b64 vcc, s[40:41]
	v_div_fmas_f32 v81, v81, v89, v86
	v_div_fixup_f32 v86, v81, v67, 1.0
	v_min_u32_e32 v67, s2, v65
	v_lshlrev_b32_e32 v80, 16, v36
	v_pk_fma_f32 v[88:89], v[86:87], v[82:83], v[58:59] op_sel_hi:[0,1,1] neg_lo:[0,0,1] neg_hi:[0,0,1]
	v_pk_fma_f32 v[90:91], v[86:87], v[84:85], v[38:39] op_sel_hi:[0,1,1] neg_lo:[0,0,1] neg_hi:[0,0,1]
	v_and_b32_e32 v81, 0xffff0000, v36
	v_sub_u32_e32 v66, v67, v66
	v_add_u32_e32 v66, 1, v66
	v_cvt_f32_i32_e32 v100, v66
	s_waitcnt vmcnt(7)
	v_lshlrev_b32_e32 v92, 16, v68
	v_and_b32_e32 v93, 0xffff0000, v68
	v_lshlrev_b32_e32 v68, 16, v69
	v_and_b32_e32 v69, 0xffff0000, v69
	v_pk_mul_f32 v[88:89], v[88:89], v[92:93]
	v_pk_mul_f32 v[68:69], v[90:91], v[68:69]
	v_pk_add_f32 v[90:91], v[80:81], 0 op_sel_hi:[1,0]
	v_lshlrev_b32_e32 v92, 16, v40
	v_and_b32_e32 v93, 0xffff0000, v40
	v_pk_add_f32 v[90:91], v[90:91], v[92:93]
	v_lshlrev_b32_e32 v94, 16, v70
	v_and_b32_e32 v95, 0xffff0000, v70
	v_pk_fma_f32 v[96:97], v[86:87], v[90:91], v[92:93] op_sel_hi:[0,1,1] neg_lo:[0,0,1] neg_hi:[0,0,1]
	v_pk_mul_f32 v[94:95], v[96:97], v[94:95]
	v_lshlrev_b32_e32 v96, 16, v37
	v_and_b32_e32 v97, 0xffff0000, v37
	v_pk_add_f32 v[36:37], v[96:97], 0 op_sel_hi:[1,0]
	v_lshlrev_b32_e32 v40, 16, v41
	v_and_b32_e32 v41, 0xffff0000, v41
	v_pk_add_f32 v[98:99], v[36:37], v[40:41]
	v_cvt_pk_bf16_f32 v66, v88, v89
	v_div_scale_f32 v88, s[0:1], v100, v100, 1.0
	v_lshlrev_b32_e32 v36, 16, v71
	v_and_b32_e32 v37, 0xffff0000, v71
	v_pk_fma_f32 v[70:71], v[86:87], v[98:99], v[40:41] op_sel_hi:[0,1,1] neg_lo:[0,0,1] neg_hi:[0,0,1]
	v_rcp_f32_e32 v89, v88
	v_pk_mul_f32 v[70:71], v[70:71], v[36:37]
	v_mov_b64_e32 v[36:37], s[38:39]
	v_mad_i64_i32 v[86:87], s[0:1], v204, s34, v[36:37]
	v_lshl_add_u64 v[86:87], v[86:87], 0, v[154:155]
	v_cvt_pk_bf16_f32 v67, v68, v69
	v_cvt_pk_bf16_f32 v68, v94, v95
	v_cvt_pk_bf16_f32 v69, v70, v71
	global_store_dwordx4 v[86:87], v[66:69], off offset:2048 nt
	s_nop 1
	v_fma_f32 v66, -v88, v89, 1.0
	v_fmac_f32_e32 v89, v66, v89
	v_div_scale_f32 v66, vcc, 1.0, v100, 1.0
	v_mul_f32_e32 v67, v66, v89
	v_fma_f32 v68, -v88, v67, v66
	v_fmac_f32_e32 v67, v68, v89
	v_fma_f32 v66, -v88, v67, v66
	v_lshlrev_b32_e32 v68, 16, v28
	v_and_b32_e32 v69, 0xffff0000, v28
	v_div_fmas_f32 v66, v66, v89, v67
	v_pk_add_f32 v[70:71], v[68:69], v[76:77] neg_lo:[0,1] neg_hi:[0,1]
	v_div_fixup_f32 v66, v66, v100, 1.0
	v_pk_add_f32 v[70:71], v[82:83], v[70:71]
	s_waitcnt vmcnt(7)
	v_lshlrev_b32_e32 v76, 16, v72
	v_and_b32_e32 v77, 0xffff0000, v72
	v_pk_fma_f32 v[82:83], v[66:67], v[70:71], v[68:69] op_sel_hi:[0,1,1] neg_lo:[0,0,1] neg_hi:[0,0,1]
	v_pk_mul_f32 v[76:77], v[82:83], v[76:77]
	v_lshlrev_b32_e32 v82, 16, v29
	v_and_b32_e32 v83, 0xffff0000, v29
	v_pk_add_f32 v[28:29], v[82:83], v[78:79] neg_lo:[0,1] neg_hi:[0,1]
	v_lshlrev_b32_e32 v88, 16, v31
	v_pk_add_f32 v[78:79], v[84:85], v[28:29]
	v_lshlrev_b32_e32 v28, 16, v73
	v_and_b32_e32 v29, 0xffff0000, v73
	v_pk_fma_f32 v[72:73], v[66:67], v[78:79], v[82:83] op_sel_hi:[0,1,1] neg_lo:[0,0,1] neg_hi:[0,0,1]
	v_lshlrev_b32_e32 v84, 16, v30
	v_and_b32_e32 v85, 0xffff0000, v30
	v_pk_mul_f32 v[72:73], v[72:73], v[28:29]
	v_pk_add_f32 v[28:29], v[84:85], v[80:81] neg_lo:[0,1] neg_hi:[0,1]
	v_and_b32_e32 v89, 0xffff0000, v31
	v_pk_add_f32 v[80:81], v[90:91], v[28:29]
	v_lshlrev_b32_e32 v28, 16, v74
	v_and_b32_e32 v29, 0xffff0000, v74
	v_pk_fma_f32 v[86:87], v[66:67], v[80:81], v[84:85] op_sel_hi:[0,1,1] neg_lo:[0,0,1] neg_hi:[0,0,1]
	v_pk_mul_f32 v[86:87], v[86:87], v[28:29]
	v_pk_add_f32 v[28:29], v[88:89], v[96:97] neg_lo:[0,1] neg_hi:[0,1]
	s_nop 0
	v_pk_add_f32 v[90:91], v[98:99], v[28:29]
	v_lshlrev_b32_e32 v28, 16, v75
	v_and_b32_e32 v29, 0xffff0000, v75
	v_pk_fma_f32 v[30:31], v[66:67], v[90:91], v[88:89] op_sel_hi:[0,1,1] neg_lo:[0,0,1] neg_hi:[0,0,1]
	v_pk_mul_f32 v[66:67], v[30:31], v[28:29]
	v_or_b32_e32 v28, 1, v204
	v_mad_i64_i32 v[28:29], s[0:1], v28, s34, v[36:37]
	v_lshl_add_u64 v[74:75], v[28:29], 0, v[154:155]
	v_min_u32_e32 v28, s2, v64
	v_sub_u32_e32 v28, v28, v65
	v_add_u32_e32 v28, 1, v28
	v_cvt_f32_i32_e32 v65, v28
	v_cvt_pk_bf16_f32 v29, v72, v73
	v_cvt_pk_bf16_f32 v28, v76, v77
	v_cvt_pk_bf16_f32 v30, v86, v87
	v_div_scale_f32 v72, s[0:1], v65, v65, 1.0
	v_rcp_f32_e32 v73, v72
	v_cvt_pk_bf16_f32 v31, v66, v67
	global_store_dwordx4 v[74:75], v[28:31], off offset:2048 nt
	s_waitcnt vmcnt(7)
	v_lshlrev_b32_e32 v66, 16, v54
	v_and_b32_e32 v67, 0xffff0000, v54
	v_fma_f32 v28, -v72, v73, 1.0
	v_fmac_f32_e32 v73, v28, v73
	v_div_scale_f32 v28, vcc, 1.0, v65, 1.0
	v_mul_f32_e32 v29, v28, v73
	v_fma_f32 v30, -v72, v29, v28
	v_fmac_f32_e32 v29, v30, v73
	v_fma_f32 v28, -v72, v29, v28
	v_lshlrev_b32_e32 v30, 16, v24
	v_and_b32_e32 v31, 0xffff0000, v24
	v_div_fmas_f32 v28, v28, v73, v29
	v_pk_add_f32 v[58:59], v[30:31], v[58:59] neg_lo:[0,1] neg_hi:[0,1]
	v_div_fixup_f32 v28, v28, v65, 1.0
	v_pk_add_f32 v[58:59], v[70:71], v[58:59]
	v_lshlrev_b32_e32 v72, 16, v26
	v_pk_fma_f32 v[70:71], v[28:29], v[58:59], v[30:31] op_sel_hi:[0,1,1] neg_lo:[0,0,1] neg_hi:[0,0,1]
	v_pk_mul_f32 v[66:67], v[70:71], v[66:67]
	v_lshlrev_b32_e32 v70, 16, v25
	v_and_b32_e32 v71, 0xffff0000, v25
	v_pk_add_f32 v[24:25], v[70:71], v[38:39] neg_lo:[0,1] neg_hi:[0,1]
	v_and_b32_e32 v73, 0xffff0000, v26
	v_pk_add_f32 v[38:39], v[78:79], v[24:25]
	v_lshlrev_b32_e32 v24, 16, v55
	v_and_b32_e32 v25, 0xffff0000, v55
	v_pk_fma_f32 v[54:55], v[28:29], v[38:39], v[70:71] op_sel_hi:[0,1,1] neg_lo:[0,0,1] neg_hi:[0,0,1]
	v_pk_mul_f32 v[54:55], v[54:55], v[24:25]
	v_pk_add_f32 v[24:25], v[72:73], v[92:93] neg_lo:[0,1] neg_hi:[0,1]
	v_lshlrev_b32_e32 v78, 16, v27
	v_pk_add_f32 v[74:75], v[80:81], v[24:25]
	v_lshlrev_b32_e32 v24, 16, v56
	v_and_b32_e32 v25, 0xffff0000, v56
	v_pk_fma_f32 v[76:77], v[28:29], v[74:75], v[72:73] op_sel_hi:[0,1,1] neg_lo:[0,0,1] neg_hi:[0,0,1]
	v_and_b32_e32 v79, 0xffff0000, v27
	v_pk_mul_f32 v[76:77], v[76:77], v[24:25]
	v_pk_add_f32 v[24:25], v[78:79], v[40:41] neg_lo:[0,1] neg_hi:[0,1]
	s_nop 0
	v_pk_add_f32 v[40:41], v[90:91], v[24:25]
	v_lshlrev_b32_e32 v24, 16, v57
	v_and_b32_e32 v25, 0xffff0000, v57
	v_pk_fma_f32 v[26:27], v[28:29], v[40:41], v[78:79] op_sel_hi:[0,1,1] neg_lo:[0,0,1] neg_hi:[0,0,1]
	v_pk_mul_f32 v[28:29], v[26:27], v[24:25]
	v_or_b32_e32 v24, 2, v204
	v_mad_i64_i32 v[24:25], s[0:1], v24, s34, v[36:37]
	v_lshl_add_u64 v[56:57], v[24:25], 0, v[154:155]
	v_min_u32_e32 v24, s2, v63
	v_sub_u32_e32 v24, v24, v64
	v_add_u32_e32 v24, 1, v24
	v_cvt_f32_i32_e32 v64, v24
	v_cvt_pk_bf16_f32 v25, v54, v55
	v_cvt_pk_bf16_f32 v24, v66, v67
	v_cvt_pk_bf16_f32 v26, v76, v77
	v_div_scale_f32 v54, s[0:1], v64, v64, 1.0
	v_rcp_f32_e32 v55, v54
	v_cvt_pk_bf16_f32 v27, v28, v29
	global_store_dwordx4 v[56:57], v[24:27], off offset:2048 nt
	s_nop 1
	v_fma_f32 v24, -v54, v55, 1.0
	v_fmac_f32_e32 v55, v24, v55
	v_div_scale_f32 v24, vcc, 1.0, v64, 1.0
	v_mul_f32_e32 v25, v24, v55
	v_fma_f32 v26, -v54, v25, v24
	v_fmac_f32_e32 v25, v26, v55
	v_fma_f32 v24, -v54, v25, v24
	v_lshlrev_b32_e32 v26, 16, v16
	v_and_b32_e32 v27, 0xffff0000, v16
	v_div_fmas_f32 v24, v24, v55, v25
	v_pk_add_f32 v[28:29], v[26:27], v[68:69] neg_lo:[0,1] neg_hi:[0,1]
	v_div_fixup_f32 v24, v24, v64, 1.0
	v_pk_add_f32 v[28:29], v[58:59], v[28:29]
	s_waitcnt vmcnt(7)
	v_lshlrev_b32_e32 v54, 16, v50
	v_and_b32_e32 v55, 0xffff0000, v50
	v_pk_fma_f32 v[56:57], v[24:25], v[28:29], v[26:27] op_sel_hi:[0,1,1] neg_lo:[0,0,1] neg_hi:[0,0,1]
	v_pk_mul_f32 v[54:55], v[56:57], v[54:55]
	v_lshlrev_b32_e32 v56, 16, v17
	v_and_b32_e32 v57, 0xffff0000, v17
	v_pk_add_f32 v[16:17], v[56:57], v[82:83] neg_lo:[0,1] neg_hi:[0,1]
	v_lshlrev_b32_e32 v58, 16, v18
	v_pk_add_f32 v[38:39], v[38:39], v[16:17]
	v_lshlrev_b32_e32 v16, 16, v51
	v_and_b32_e32 v17, 0xffff0000, v51
	v_pk_fma_f32 v[50:51], v[24:25], v[38:39], v[56:57] op_sel_hi:[0,1,1] neg_lo:[0,0,1] neg_hi:[0,0,1]
	v_and_b32_e32 v59, 0xffff0000, v18
	v_pk_mul_f32 v[50:51], v[50:51], v[16:17]
	v_pk_add_f32 v[16:17], v[58:59], v[84:85] neg_lo:[0,1] neg_hi:[0,1]
	v_lshlrev_b32_e32 v68, 16, v19
	v_pk_add_f32 v[64:65], v[74:75], v[16:17]
	v_lshlrev_b32_e32 v16, 16, v52
	v_and_b32_e32 v17, 0xffff0000, v52
	v_pk_fma_f32 v[66:67], v[24:25], v[64:65], v[58:59] op_sel_hi:[0,1,1] neg_lo:[0,0,1] neg_hi:[0,0,1]
	v_and_b32_e32 v69, 0xffff0000, v19
	v_pk_mul_f32 v[66:67], v[66:67], v[16:17]
	v_pk_add_f32 v[16:17], v[68:69], v[88:89] neg_lo:[0,1] neg_hi:[0,1]
	s_nop 0
	v_pk_add_f32 v[40:41], v[40:41], v[16:17]
	v_lshlrev_b32_e32 v16, 16, v53
	v_and_b32_e32 v17, 0xffff0000, v53
	v_pk_fma_f32 v[18:19], v[24:25], v[40:41], v[68:69] op_sel_hi:[0,1,1] neg_lo:[0,0,1] neg_hi:[0,0,1]
	v_pk_mul_f32 v[24:25], v[18:19], v[16:17]
	v_or_b32_e32 v16, 3, v204
	v_mad_i64_i32 v[16:17], s[0:1], v16, s34, v[36:37]
	v_lshl_add_u64 v[52:53], v[16:17], 0, v[154:155]
	v_min_u32_e32 v16, s2, v62
	v_sub_u32_e32 v16, v16, v63
	v_add_u32_e32 v16, 1, v16
	v_cvt_f32_i32_e32 v63, v16
	v_cvt_pk_bf16_f32 v17, v50, v51
	v_cvt_pk_bf16_f32 v16, v54, v55
	v_cvt_pk_bf16_f32 v18, v66, v67
	v_div_scale_f32 v50, s[0:1], v63, v63, 1.0
	v_rcp_f32_e32 v51, v50
	v_cvt_pk_bf16_f32 v19, v24, v25
	global_store_dwordx4 v[52:53], v[16:19], off offset:2048 nt
	s_nop 1
	v_fma_f32 v16, -v50, v51, 1.0
	v_fmac_f32_e32 v51, v16, v51
	v_div_scale_f32 v16, vcc, 1.0, v63, 1.0
	v_mul_f32_e32 v17, v16, v51
	v_fma_f32 v18, -v50, v17, v16
	v_fmac_f32_e32 v17, v18, v51
	v_fma_f32 v16, -v50, v17, v16
	v_lshlrev_b32_e32 v18, 16, v12
	v_and_b32_e32 v19, 0xffff0000, v12
	v_div_fmas_f32 v16, v16, v51, v17
	v_pk_add_f32 v[24:25], v[18:19], v[30:31] neg_lo:[0,1] neg_hi:[0,1]
	v_div_fixup_f32 v16, v16, v63, 1.0
	v_pk_add_f32 v[24:25], v[28:29], v[24:25]
	s_waitcnt vmcnt(7)
	v_lshlrev_b32_e32 v28, 16, v46
	v_and_b32_e32 v29, 0xffff0000, v46
	v_pk_fma_f32 v[30:31], v[16:17], v[24:25], v[18:19] op_sel_hi:[0,1,1] neg_lo:[0,0,1] neg_hi:[0,0,1]
	v_pk_mul_f32 v[28:29], v[30:31], v[28:29]
	v_lshlrev_b32_e32 v30, 16, v13
	v_and_b32_e32 v31, 0xffff0000, v13
	v_pk_add_f32 v[12:13], v[30:31], v[70:71] neg_lo:[0,1] neg_hi:[0,1]
	v_lshlrev_b32_e32 v50, 16, v14
	v_pk_add_f32 v[38:39], v[38:39], v[12:13]
	v_lshlrev_b32_e32 v12, 16, v47
	v_and_b32_e32 v13, 0xffff0000, v47
	v_pk_fma_f32 v[46:47], v[16:17], v[38:39], v[30:31] op_sel_hi:[0,1,1] neg_lo:[0,0,1] neg_hi:[0,0,1]
	v_and_b32_e32 v51, 0xffff0000, v14
	v_pk_mul_f32 v[46:47], v[46:47], v[12:13]
	v_pk_add_f32 v[12:13], v[50:51], v[72:73] neg_lo:[0,1] neg_hi:[0,1]
	s_nop 0
	v_pk_add_f32 v[52:53], v[64:65], v[12:13]
	v_lshlrev_b32_e32 v12, 16, v48
	v_and_b32_e32 v13, 0xffff0000, v48
	v_pk_fma_f32 v[54:55], v[16:17], v[52:53], v[50:51] op_sel_hi:[0,1,1] neg_lo:[0,0,1] neg_hi:[0,0,1]
	v_lshlrev_b32_e32 v64, 16, v15
	v_and_b32_e32 v65, 0xffff0000, v15
	v_pk_mul_f32 v[54:55], v[54:55], v[12:13]
	v_pk_add_f32 v[12:13], v[64:65], v[78:79] neg_lo:[0,1] neg_hi:[0,1]
	s_nop 0
	v_pk_add_f32 v[40:41], v[40:41], v[12:13]
	v_lshlrev_b32_e32 v12, 16, v49
	v_and_b32_e32 v13, 0xffff0000, v49
	v_pk_fma_f32 v[14:15], v[16:17], v[40:41], v[64:65] op_sel_hi:[0,1,1] neg_lo:[0,0,1] neg_hi:[0,0,1]
	v_pk_mul_f32 v[16:17], v[14:15], v[12:13]
	v_or_b32_e32 v12, 4, v204
	v_mad_i64_i32 v[12:13], s[0:1], v12, s34, v[36:37]
	v_lshl_add_u64 v[48:49], v[12:13], 0, v[154:155]
	v_min_u32_e32 v12, s2, v61
	v_sub_u32_e32 v12, v12, v62
	v_add_u32_e32 v12, 1, v12
	v_cvt_f32_i32_e32 v62, v12
	v_cvt_pk_bf16_f32 v12, v28, v29
	v_cvt_pk_bf16_f32 v13, v46, v47
	v_cvt_pk_bf16_f32 v14, v54, v55
	v_div_scale_f32 v28, s[0:1], v62, v62, 1.0
	v_rcp_f32_e32 v29, v28
	v_cvt_pk_bf16_f32 v15, v16, v17
	global_store_dwordx4 v[48:49], v[12:15], off offset:2048 nt
	s_nop 1
	v_fma_f32 v12, -v28, v29, 1.0
	v_fmac_f32_e32 v29, v12, v29
	v_div_scale_f32 v12, vcc, 1.0, v62, 1.0
	v_mul_f32_e32 v13, v12, v29
	v_fma_f32 v14, -v28, v13, v12
	v_fmac_f32_e32 v13, v14, v29
	v_fma_f32 v12, -v28, v13, v12
	v_lshlrev_b32_e32 v14, 16, v8
	v_and_b32_e32 v15, 0xffff0000, v8
	v_div_fmas_f32 v12, v12, v29, v13
	v_pk_add_f32 v[16:17], v[14:15], v[26:27] neg_lo:[0,1] neg_hi:[0,1]
	v_div_fixup_f32 v12, v12, v62, 1.0
	v_pk_add_f32 v[16:17], v[24:25], v[16:17]
	s_waitcnt vmcnt(7)
	v_lshlrev_b32_e32 v24, 16, v42
	v_and_b32_e32 v25, 0xffff0000, v42
	v_pk_fma_f32 v[26:27], v[12:13], v[16:17], v[14:15] op_sel_hi:[0,1,1] neg_lo:[0,0,1] neg_hi:[0,0,1]
	v_pk_mul_f32 v[24:25], v[26:27], v[24:25]
	v_lshlrev_b32_e32 v26, 16, v9
	v_and_b32_e32 v27, 0xffff0000, v9
	v_pk_add_f32 v[8:9], v[26:27], v[56:57] neg_lo:[0,1] neg_hi:[0,1]
	v_lshlrev_b32_e32 v42, 16, v10
	v_pk_add_f32 v[28:29], v[38:39], v[8:9]
	v_lshlrev_b32_e32 v8, 16, v43
	v_and_b32_e32 v9, 0xffff0000, v43
	v_pk_fma_f32 v[38:39], v[12:13], v[28:29], v[26:27] op_sel_hi:[0,1,1] neg_lo:[0,0,1] neg_hi:[0,0,1]
	v_and_b32_e32 v43, 0xffff0000, v10
	v_pk_mul_f32 v[38:39], v[38:39], v[8:9]
	v_pk_add_f32 v[8:9], v[42:43], v[58:59] neg_lo:[0,1] neg_hi:[0,1]
	s_nop 0
	v_pk_add_f32 v[46:47], v[52:53], v[8:9]
	v_lshlrev_b32_e32 v8, 16, v44
	v_and_b32_e32 v9, 0xffff0000, v44
	v_pk_fma_f32 v[48:49], v[12:13], v[46:47], v[42:43] op_sel_hi:[0,1,1] neg_lo:[0,0,1] neg_hi:[0,0,1]
	v_lshlrev_b32_e32 v52, 16, v11
	v_and_b32_e32 v53, 0xffff0000, v11
	v_pk_mul_f32 v[48:49], v[48:49], v[8:9]
	v_pk_add_f32 v[8:9], v[52:53], v[68:69] neg_lo:[0,1] neg_hi:[0,1]
	s_nop 0
	v_pk_add_f32 v[40:41], v[40:41], v[8:9]
	v_lshlrev_b32_e32 v8, 16, v45
	v_and_b32_e32 v9, 0xffff0000, v45
	v_pk_fma_f32 v[10:11], v[12:13], v[40:41], v[52:53] op_sel_hi:[0,1,1] neg_lo:[0,0,1] neg_hi:[0,0,1]
	v_pk_mul_f32 v[12:13], v[10:11], v[8:9]
	v_or_b32_e32 v8, 5, v204
	v_mad_i64_i32 v[8:9], s[0:1], v8, s34, v[36:37]
	v_lshl_add_u64 v[44:45], v[8:9], 0, v[154:155]
	v_min_u32_e32 v8, s2, v60
	v_sub_u32_e32 v8, v8, v61
	v_add_u32_e32 v8, 1, v8
	v_cvt_f32_i32_e32 v54, v8
	v_cvt_pk_bf16_f32 v8, v24, v25
	v_cvt_pk_bf16_f32 v9, v38, v39
	v_cvt_pk_bf16_f32 v10, v48, v49
	v_div_scale_f32 v24, s[0:1], v54, v54, 1.0
	v_rcp_f32_e32 v25, v24
	v_cvt_pk_bf16_f32 v11, v12, v13
	global_store_dwordx4 v[44:45], v[8:11], off offset:2048 nt
	s_nop 1
	v_fma_f32 v8, -v24, v25, 1.0
	v_fmac_f32_e32 v25, v8, v25
	v_div_scale_f32 v8, vcc, 1.0, v54, 1.0
	v_mul_f32_e32 v9, v8, v25
	v_fma_f32 v10, -v24, v9, v8
	v_fmac_f32_e32 v9, v10, v25
	v_fma_f32 v8, -v24, v9, v8
	v_lshlrev_b32_e32 v10, 16, v4
	v_and_b32_e32 v11, 0xffff0000, v4
	v_div_fmas_f32 v8, v8, v25, v9
	v_pk_add_f32 v[12:13], v[10:11], v[18:19] neg_lo:[0,1] neg_hi:[0,1]
	v_div_fixup_f32 v8, v8, v54, 1.0
	v_pk_add_f32 v[12:13], v[16:17], v[12:13]
	s_waitcnt vmcnt(7)
	v_lshlrev_b32_e32 v16, 16, v32
	v_and_b32_e32 v17, 0xffff0000, v32
	v_pk_fma_f32 v[10:11], v[8:9], v[12:13], v[10:11] op_sel_hi:[0,1,1] neg_lo:[0,0,1] neg_hi:[0,0,1]
	v_lshlrev_b32_e32 v4, 16, v5
	v_and_b32_e32 v5, 0xffff0000, v5
	v_pk_mul_f32 v[10:11], v[10:11], v[16:17]
	v_pk_add_f32 v[16:17], v[4:5], v[30:31] neg_lo:[0,1] neg_hi:[0,1]
	v_lshlrev_b32_e32 v18, 16, v33
	v_pk_add_f32 v[16:17], v[28:29], v[16:17]
	v_and_b32_e32 v19, 0xffff0000, v33
	v_pk_fma_f32 v[4:5], v[8:9], v[16:17], v[4:5] op_sel_hi:[0,1,1] neg_lo:[0,0,1] neg_hi:[0,0,1]
	v_pk_mul_f32 v[18:19], v[4:5], v[18:19]
	v_lshlrev_b32_e32 v4, 16, v6
	v_and_b32_e32 v5, 0xffff0000, v6
	v_pk_add_f32 v[24:25], v[4:5], v[50:51] neg_lo:[0,1] neg_hi:[0,1]
	v_lshlrev_b32_e32 v28, 16, v34
	v_pk_add_f32 v[24:25], v[46:47], v[24:25]
	v_and_b32_e32 v29, 0xffff0000, v34
	v_pk_fma_f32 v[4:5], v[8:9], v[24:25], v[4:5] op_sel_hi:[0,1,1] neg_lo:[0,0,1] neg_hi:[0,0,1]
	v_pk_mul_f32 v[28:29], v[4:5], v[28:29]
	v_lshlrev_b32_e32 v4, 16, v7
	v_and_b32_e32 v5, 0xffff0000, v7
	v_pk_add_f32 v[6:7], v[4:5], v[64:65] neg_lo:[0,1] neg_hi:[0,1]
	s_nop 0
	v_pk_add_f32 v[30:31], v[40:41], v[6:7]
	v_lshlrev_b32_e32 v6, 16, v35
	v_and_b32_e32 v7, 0xffff0000, v35
	v_pk_fma_f32 v[4:5], v[8:9], v[30:31], v[4:5] op_sel_hi:[0,1,1] neg_lo:[0,0,1] neg_hi:[0,0,1]
	v_pk_mul_f32 v[8:9], v[4:5], v[6:7]
	v_or_b32_e32 v4, 6, v204
	v_mad_i64_i32 v[4:5], s[0:1], v4, s34, v[36:37]
	v_lshl_add_u64 v[32:33], v[4:5], 0, v[154:155]
	v_add_u32_e32 v4, 8, v206
	v_min_u32_e32 v4, s2, v4
	v_sub_u32_e32 v4, v4, v60
	v_add_u32_e32 v4, 1, v4
	v_cvt_f32_i32_e32 v34, v4
	v_cvt_pk_bf16_f32 v4, v10, v11
	v_cvt_pk_bf16_f32 v5, v18, v19
	v_cvt_pk_bf16_f32 v6, v28, v29
	v_div_scale_f32 v10, s[0:1], v34, v34, 1.0
	v_rcp_f32_e32 v11, v10
	v_cvt_pk_bf16_f32 v7, v8, v9
	global_store_dwordx4 v[32:33], v[4:7], off offset:2048 nt
	s_nop 1
	v_fma_f32 v4, -v10, v11, 1.0
	v_fmac_f32_e32 v11, v4, v11
	v_div_scale_f32 v4, vcc, 1.0, v34, 1.0
	v_mul_f32_e32 v5, v4, v11
	v_fma_f32 v6, -v10, v5, v4
	v_fmac_f32_e32 v5, v6, v11
	v_fma_f32 v4, -v10, v5, v4
	v_lshlrev_b32_e32 v6, 16, v0
	v_and_b32_e32 v7, 0xffff0000, v0
	v_div_fmas_f32 v4, v4, v11, v5
	v_pk_add_f32 v[8:9], v[6:7], v[14:15] neg_lo:[0,1] neg_hi:[0,1]
	v_div_fixup_f32 v4, v4, v34, 1.0
	v_pk_add_f32 v[8:9], v[12:13], v[8:9]
	v_lshlrev_b32_e32 v0, 16, v1
	v_and_b32_e32 v1, 0xffff0000, v1
	v_pk_fma_f32 v[6:7], v[4:5], v[8:9], v[6:7] op_sel_hi:[0,1,1] neg_lo:[0,0,1] neg_hi:[0,0,1]
	v_pk_add_f32 v[8:9], v[0:1], v[26:27] neg_lo:[0,1] neg_hi:[0,1]
	s_waitcnt vmcnt(7)
	v_lshlrev_b32_e32 v10, 16, v20
	v_and_b32_e32 v11, 0xffff0000, v20
	v_pk_add_f32 v[8:9], v[16:17], v[8:9]
	v_pk_mul_f32 v[6:7], v[6:7], v[10:11]
	v_lshlrev_b32_e32 v10, 16, v21
	v_and_b32_e32 v11, 0xffff0000, v21
	v_pk_fma_f32 v[0:1], v[4:5], v[8:9], v[0:1] op_sel_hi:[0,1,1] neg_lo:[0,0,1] neg_hi:[0,0,1]
	v_pk_mul_f32 v[8:9], v[0:1], v[10:11]
	v_lshlrev_b32_e32 v0, 16, v2
	v_and_b32_e32 v1, 0xffff0000, v2
	v_pk_add_f32 v[10:11], v[0:1], v[42:43] neg_lo:[0,1] neg_hi:[0,1]
	v_lshlrev_b32_e32 v12, 16, v22
	v_pk_add_f32 v[10:11], v[24:25], v[10:11]
	v_and_b32_e32 v13, 0xffff0000, v22
	v_pk_fma_f32 v[0:1], v[4:5], v[10:11], v[0:1] op_sel_hi:[0,1,1] neg_lo:[0,0,1] neg_hi:[0,0,1]
	v_pk_mul_f32 v[10:11], v[0:1], v[12:13]
	v_lshlrev_b32_e32 v0, 16, v3
	v_and_b32_e32 v1, 0xffff0000, v3
	v_pk_add_f32 v[2:3], v[0:1], v[52:53] neg_lo:[0,1] neg_hi:[0,1]
	v_lshlrev_b32_e32 v12, 16, v23
	v_pk_add_f32 v[2:3], v[30:31], v[2:3]
	v_and_b32_e32 v13, 0xffff0000, v23
	v_pk_fma_f32 v[0:1], v[4:5], v[2:3], v[0:1] op_sel_hi:[0,1,1] neg_lo:[0,0,1] neg_hi:[0,0,1]
	v_pk_mul_f32 v[4:5], v[0:1], v[12:13]
	v_or_b32_e32 v0, 7, v204
	v_mad_i64_i32 v[0:1], s[0:1], v0, s34, v[36:37]
	v_lshl_add_u64 v[12:13], v[0:1], 0, v[154:155]
	v_cvt_pk_bf16_f32 v0, v6, v7
	v_cvt_pk_bf16_f32 v1, v8, v9
	v_cvt_pk_bf16_f32 v2, v10, v11
	v_cvt_pk_bf16_f32 v3, v4, v5
	global_store_dwordx4 v[12:13], v[0:3], off offset:2048 nt
	s_branch .LBB0_148
